# SSM pass 1 chunk loop: end state by per-lane weight (A^8)^(15-j) table + DPP row sum + (A^8)^16 carry instead of the full 16-lane inclusive scan (pass 1 only needs chunk end states)
# speedup vs baseline: 1.0086x; 1.0048x over previous
; #define LAS __attribute__((address_space(3)))
; template <bool PASS2>
; __device__ __forceinline__ void ssm_phase(const Params& p, const Frame& F0) {
;     ...
;         { const u32x4* src = (const u32x4*)((const bf16_t*)(p.ws + WS_SSMW) + (size_t)g * SSM_FRAG_ELEMS);
;           for (int e = F.tid; e < SSM_FRAG_ELEMS / 8; e += 512) ((LAS u32x4*)F.lds)[e] = src[e];
;           if (F.tid < 64) ((LAS f32x2*)(F.lds + SSM_M1_OFF))[F.tid] = ((const f32x2*)(p.ws + WS_M1))[g * 64 + F.tid]; }
;         __syncthreads();
;         const LAS bf16x8* frag = (const LAS bf16x8*)F.lds + lane;
;         const LAS f32x4* m1t = (const LAS f32x4*)(F.lds + SSM_M1_OFF) + 2 * gq;
;         const int b = subset >> 2, wch = (subset & 3) * 8 + F.wave;
;     ...
;         bf16x8 uf[4], ufn[4]; u32x2 uw[8], uwn[8];
;         SSM_LOAD_U(uf, uw, 0)
.LBB0_524:
	s_or_b64 exec, exec, s[16:17]
	s_lshl_b32 s0, s23, 2
	s_and_b32 s0, s0, 28
	s_and_b32 s1, s24, 3
	s_or_b32 s16, s0, s1
	s_and_saveexec_b64 s[0:1], s[4:5]
	s_cbranch_execz .LBB0_526
	v_lshl_add_u32 v0, s16, 6, v36
	v_ashrrev_i32_e32 v1, 31, v0
	v_lshl_add_u64 v[0:1], v[0:1], 3, s[12:13]
	global_load_dwordx2 v[0:1], v[0:1], off
	s_waitcnt vmcnt(0)
	ds_write_b64 v104, v[0:1]
	v_bfe_u32 v4, v104, 3, 1
	v_lshlrev_b32_e32 v4, 2, v4
	v_sub_u32_e32 v4, v104, v4
	v_mul_f32_e32 v5, v1, v1
	v_add_f32_e32 v6, v0, v0
	v_fma_f32 v7, v0, v0, -v5
	v_mul_f32_e32 v8, v6, v1
	ds_write_b32 v4, v7 offset:512
	ds_write_b32 v4, v8 offset:520
	v_mul_f32_e32 v5, v8, v8
	v_add_f32_e32 v6, v7, v7
	v_fma_f32 v9, v7, v7, -v5
	v_mul_f32_e32 v10, v6, v8
	ds_write_b32 v4, v9 offset:1024
	ds_write_b32 v4, v10 offset:1032
	v_mul_f32_e32 v5, v10, v10
	v_add_f32_e32 v6, v9, v9
	v_fma_f32 v7, v9, v9, -v5
	v_mul_f32_e32 v8, v6, v10
	ds_write_b32 v4, v7 offset:1536
	ds_write_b32 v4, v8 offset:1544
	v_mov_b32_e32 v11, 1.0
	v_mov_b32_e32 v12, 0
	ds_write_b32 v4, v11 offset:10240
	ds_write_b32 v4, v12 offset:10248
	v_mul_f32_e32 v13, v12, v1
	v_mul_f32_e32 v14, v11, v1
	v_fma_f32 v11, v11, v0, -v13
	v_fma_f32 v12, v12, v0, v14
	ds_write_b32 v4, v11 offset:9728
	ds_write_b32 v4, v12 offset:9736
	v_mul_f32_e32 v13, v12, v1
	v_mul_f32_e32 v14, v11, v1
	v_fma_f32 v11, v11, v0, -v13
	v_fma_f32 v12, v12, v0, v14
	ds_write_b32 v4, v11 offset:9216
	ds_write_b32 v4, v12 offset:9224
	v_mul_f32_e32 v13, v12, v1
	v_mul_f32_e32 v14, v11, v1
	v_fma_f32 v11, v11, v0, -v13
	v_fma_f32 v12, v12, v0, v14
	ds_write_b32 v4, v11 offset:8704
	ds_write_b32 v4, v12 offset:8712
	v_mul_f32_e32 v13, v12, v1
	v_mul_f32_e32 v14, v11, v1
	v_fma_f32 v11, v11, v0, -v13
	v_fma_f32 v12, v12, v0, v14
	ds_write_b32 v4, v11 offset:8192
	ds_write_b32 v4, v12 offset:8200
	v_mul_f32_e32 v13, v12, v1
	v_mul_f32_e32 v14, v11, v1
	v_fma_f32 v11, v11, v0, -v13
	v_fma_f32 v12, v12, v0, v14
	ds_write_b32 v4, v11 offset:7680
	ds_write_b32 v4, v12 offset:7688
	v_mul_f32_e32 v13, v12, v1
	v_mul_f32_e32 v14, v11, v1
	v_fma_f32 v11, v11, v0, -v13
	v_fma_f32 v12, v12, v0, v14
	ds_write_b32 v4, v11 offset:7168
	ds_write_b32 v4, v12 offset:7176
	v_mul_f32_e32 v13, v12, v1
	v_mul_f32_e32 v14, v11, v1
	v_fma_f32 v11, v11, v0, -v13
	v_fma_f32 v12, v12, v0, v14
	ds_write_b32 v4, v11 offset:6656
	ds_write_b32 v4, v12 offset:6664
	v_mul_f32_e32 v13, v12, v1
	v_mul_f32_e32 v14, v11, v1
	v_fma_f32 v11, v11, v0, -v13
	v_fma_f32 v12, v12, v0, v14
	ds_write_b32 v4, v11 offset:6144
	ds_write_b32 v4, v12 offset:6152
	v_mul_f32_e32 v13, v12, v1
	v_mul_f32_e32 v14, v11, v1
	v_fma_f32 v11, v11, v0, -v13
	v_fma_f32 v12, v12, v0, v14
	ds_write_b32 v4, v11 offset:5632
	ds_write_b32 v4, v12 offset:5640
	v_mul_f32_e32 v13, v12, v1
	v_mul_f32_e32 v14, v11, v1
	v_fma_f32 v11, v11, v0, -v13
	v_fma_f32 v12, v12, v0, v14
	ds_write_b32 v4, v11 offset:5120
	ds_write_b32 v4, v12 offset:5128
	v_mul_f32_e32 v13, v12, v1
	v_mul_f32_e32 v14, v11, v1
	v_fma_f32 v11, v11, v0, -v13
	v_fma_f32 v12, v12, v0, v14
	ds_write_b32 v4, v11 offset:4608
	ds_write_b32 v4, v12 offset:4616
	v_mul_f32_e32 v13, v12, v1
	v_mul_f32_e32 v14, v11, v1
	v_fma_f32 v11, v11, v0, -v13
	v_fma_f32 v12, v12, v0, v14
	ds_write_b32 v4, v11 offset:4096
	ds_write_b32 v4, v12 offset:4104
	v_mul_f32_e32 v13, v12, v1
	v_mul_f32_e32 v14, v11, v1
	v_fma_f32 v11, v11, v0, -v13
	v_fma_f32 v12, v12, v0, v14
	ds_write_b32 v4, v11 offset:3584
	ds_write_b32 v4, v12 offset:3592
	v_mul_f32_e32 v13, v12, v1
	v_mul_f32_e32 v14, v11, v1
	v_fma_f32 v11, v11, v0, -v13
	v_fma_f32 v12, v12, v0, v14
	ds_write_b32 v4, v11 offset:3072
	ds_write_b32 v4, v12 offset:3080
	v_mul_f32_e32 v13, v12, v1
	v_mul_f32_e32 v14, v11, v1
	v_fma_f32 v11, v11, v0, -v13
	v_fma_f32 v12, v12, v0, v14
	ds_write_b32 v4, v11 offset:2560
	ds_write_b32 v4, v12 offset:2568
	v_mul_f32_e32 v13, v12, v1
	v_mul_f32_e32 v14, v11, v1
	v_fma_f32 v11, v11, v0, -v13
	v_fma_f32 v12, v12, v0, v14
	ds_write_b32 v4, v11 offset:2048
	ds_write_b32 v4, v12 offset:2056
.LBB0_526:
	s_or_b64 exec, exec, s[0:1]
	s_lshr_b32 s0, s23, 2
	s_and_b32 s18, s0, 24
	s_ashr_i32 s17, s23, 7
	s_add_i32 s18, s18, s3
	s_lshl_b32 s0, s17, 14
	s_lshl_b32 s1, s18, 9
	s_add_i32 s1, s1, s0
	v_or_b32_e32 v0, s1, v106
	v_or_b32_e32 v4, 2, v0
	s_lshl_b32 s10, s16, 5
	v_ashrrev_i32_e32 v1, 31, v0
	v_ashrrev_i32_e32 v5, 31, v4
	v_lshl_add_u64 v[64:65], v[38:39], 0, s[10:11]
	v_lshlrev_b64 v[2:3], 10, v[0:1]
	v_lshlrev_b64 v[4:5], 10, v[4:5]
	v_lshl_add_u64 v[2:3], v[64:65], 0, v[2:3]
	v_lshl_add_u64 v[4:5], v[64:65], 0, v[4:5]
	s_waitcnt lgkmcnt(0)
	s_barrier
; template <bool PASS2>
; __device__ __forceinline__ void ssm_phase(const Params& p, const Frame& F0) {
;     ...
;         f32x4 xs[8];
; #pragma unroll
;         for (int i = 0; i < 8; ++i) xs[i] = (f32x4){0.f, 0.f, 0.f, 0.f};
;     ...
;         bf16x8 uf[4], ufn[4]; u32x2 uw[8], uwn[8];
;         SSM_LOAD_U(uf, uw, 0)
;         for (int cc = 0; cc < nch; ++cc) {
;             asm volatile("" ::: "memory");
;             const bool samp = (cc == 4);
;             const int row0 = SSM_ROW0(cc), nsub = SSM_NSUB(cc), js = jsamp;
;             if (samp) {
; #pragma unroll
;                 for (int i = 0; i < 4; ++i) { xs[i] = *(const f32x4*)(p.in[2] + (size_t)(js * NG + g) * 64 + 16 * i + 4 * gq); xs[i + 4] = *(const f32x4*)(p.in[3] + (size_t)(js * NG + g) * 64 + 16 * i + 4 * gq); } }
;             if (cc + 1 < nch) SSM_LOAD_U(ufn, uwn, cc + 1)
;             unsigned hw[4][4];
; #pragma unroll
;             for (int i = 0; i < 4; ++i) {
;                 __builtin_amdgcn_sched_barrier(0);
;                 f32x4 Er = (f32x4){0.f, 0.f, 0.f, 0.f}, Ei = Er;
; #pragma unroll
;                 for (int ks = 0; ks < 4; ++ks) { Er = __builtin_amdgcn_mfma_f32_16x16x32_bf16(frag[(i * 4 + ks) * 64], uf[ks], Er, 0, 0, 0);
;                                                  Ei = __builtin_amdgcn_mfma_f32_16x16x32_bf16(frag[((i + 4) * 4 + ks) * 64], uf[ks], Ei, 0, 0, 0); }
	global_load_dwordx4 v[12:15], v[2:3], off
	s_nop 0
	global_load_dwordx4 v[4:7], v[4:5], off
	v_or_b32_e32 v2, 4, v0
	v_or_b32_e32 v0, 6, v0
	v_ashrrev_i32_e32 v3, 31, v2
	v_ashrrev_i32_e32 v1, 31, v0
	v_lshlrev_b64 v[2:3], 10, v[2:3]
	v_lshlrev_b64 v[0:1], 10, v[0:1]
	v_lshl_add_u64 v[2:3], v[64:65], 0, v[2:3]
	v_lshl_add_u64 v[0:1], v[64:65], 0, v[0:1]
	global_load_dwordx4 v[8:11], v[2:3], off
	s_nop 0
	global_load_dwordx4 v[0:3], v[0:1], off
	s_lshl_b32 s1, s23, 7
	s_and_b32 s1, s1, 0x3000
	s_or_b32 s0, s1, s0
	v_add_u32_e32 v80, s0, v37
	s_mov_b32 s0, 0
	v_mov_b32_e32 v44, 0
	v_mov_b32_e32 v45, 0
	v_mov_b32_e32 v48, 0
	v_mov_b32_e32 v49, 0
	v_mov_b32_e32 v52, 0
	v_mov_b32_e32 v53, 0
	v_mov_b32_e32 v56, 0
	v_mov_b32_e32 v57, 0
	v_mov_b32_e32 v60, 0
	v_mov_b32_e32 v61, 0
	v_mov_b32_e32 v66, 0
	v_mov_b32_e32 v67, 0
	v_mov_b32_e32 v70, 0
	v_mov_b32_e32 v71, 0
	v_mov_b32_e32 v74, 0
	v_mov_b32_e32 v75, 0
	v_mov_b32_e32 v46, 0
	v_mov_b32_e32 v47, 0
	v_mov_b32_e32 v50, 0
	v_mov_b32_e32 v51, 0
	v_mov_b32_e32 v54, 0
	v_mov_b32_e32 v55, 0
	v_mov_b32_e32 v58, 0
	v_mov_b32_e32 v59, 0
	v_mov_b32_e32 v62, 0
	v_mov_b32_e32 v63, 0
	v_mov_b32_e32 v68, 0
	v_mov_b32_e32 v69, 0
	v_mov_b32_e32 v72, 0
	v_mov_b32_e32 v73, 0
	v_mov_b32_e32 v76, 0
	v_mov_b32_e32 v77, 0
	ds_read_b128 v[130:133], v105
	ds_read_b128 v[134:137], v105 offset:1024
	ds_read_b128 v[138:141], v105 offset:2048
	ds_read_b128 v[142:145], v105 offset:3072
	ds_read_b128 v[146:149], v105 offset:4096
	ds_read_b128 v[150:153], v105 offset:5120
	ds_read_b128 v[154:157], v105 offset:6144
	ds_read_b128 v[158:161], v105 offset:7168
	ds_read_b128 v[162:165], v105 offset:8192
	ds_read_b128 v[166:169], v105 offset:9216
	ds_read_b128 v[170:173], v105 offset:10240
	ds_read_b128 v[174:177], v105 offset:11264
	ds_read_b128 v[178:181], v105 offset:12288
	ds_read_b128 v[182:185], v105 offset:13312
	ds_read_b128 v[186:189], v105 offset:14336
	ds_read_b128 v[190:193], v105 offset:15360
	ds_read_b128 v[194:197], v105 offset:16384
	ds_read_b128 v[198:201], v105 offset:17408
	ds_read_b128 v[204:207], v105 offset:18432
	ds_read_b128 v[208:211], v105 offset:19456
	ds_read_b128 v[212:215], v105 offset:20480
	ds_read_b128 v[216:219], v105 offset:21504
	ds_read_b128 v[220:223], v105 offset:22528
	ds_read_b128 v[224:227], v105 offset:23552
	ds_read_b128 v[228:231], v105 offset:24576
	ds_read_b128 v[232:235], v105 offset:25600
	ds_read_b128 v[236:239], v105 offset:26624
	ds_read_b128 v[240:243], v105 offset:27648
	ds_read_b128 v[244:247], v105 offset:28672
	ds_read_b128 v[248:251], v105 offset:29696
	ds_read_b128 v[114:117], v105 offset:30720
	ds_read_b128 v[118:121], v105 offset:31744
	s_waitcnt lgkmcnt(0)
	v_and_b32_e32 v110, 15, v202
	v_lshl_add_u32 v110, v110, 9, v109
.LBB0_527:
	s_waitcnt vmcnt(0)
	v_mov_b64_e32 v[18:19], v[2:3]
	v_mov_b64_e32 v[26:27], v[6:7]
	v_mov_b64_e32 v[16:17], v[0:1]
	v_add_u32_e32 v1, s0, v80
	v_mov_b64_e32 v[24:25], v[4:5]
	v_add_u32_e32 v0, 0x80, v1
	v_add_u32_e32 v2, 0x82, v1
	v_add_u32_e32 v4, 0x84, v1
	v_add_u32_e32 v6, 0x86, v1
	v_ashrrev_i32_e32 v1, 31, v0
	v_ashrrev_i32_e32 v3, 31, v2
	v_ashrrev_i32_e32 v5, 31, v4
	v_mov_b64_e32 v[22:23], v[10:11]
	v_ashrrev_i32_e32 v7, 31, v6
	v_lshlrev_b64 v[0:1], 10, v[0:1]
	v_lshlrev_b64 v[2:3], 10, v[2:3]
	v_lshlrev_b64 v[4:5], 10, v[4:5]
	v_mov_b64_e32 v[30:31], v[14:15]
	v_mov_b64_e32 v[20:21], v[8:9]
	v_lshlrev_b64 v[6:7], 10, v[6:7]
	v_lshl_add_u64 v[0:1], v[64:65], 0, v[0:1]
	v_lshl_add_u64 v[2:3], v[64:65], 0, v[2:3]
	v_lshl_add_u64 v[8:9], v[64:65], 0, v[4:5]
	v_mov_b64_e32 v[28:29], v[12:13]
	v_lshl_add_u64 v[32:33], v[64:65], 0, v[6:7]
	global_load_dwordx4 v[12:15], v[0:1], off
	global_load_dwordx4 v[4:7], v[2:3], off
	s_nop 0
	global_load_dwordx4 v[8:11], v[8:9], off
	s_nop 0
	global_load_dwordx4 v[0:3], v[32:33], off
	ds_read_b128 v[90:93], v110 offset:2560
	ds_read_b128 v[94:97], v110 offset:2576
	v_mfma_f32_16x16x32_bf16 v[32:35], v[130:133], v[28:31], 0
	v_mfma_f32_16x16x32_bf16 v[32:35], v[134:137], v[24:27], v[32:35]
	v_mfma_f32_16x16x32_bf16 v[82:85], v[194:197], v[28:31], 0
	v_mfma_f32_16x16x32_bf16 v[82:85], v[198:201], v[24:27], v[82:85]
	v_mfma_f32_16x16x32_bf16 v[32:35], v[138:141], v[20:23], v[32:35]
	v_mfma_f32_16x16x32_bf16 v[82:85], v[204:207], v[20:23], v[82:85]
	v_mfma_f32_16x16x32_bf16 v[86:89], v[142:145], v[16:19], v[32:35]
	v_mfma_f32_16x16x32_bf16 v[82:85], v[208:211], v[16:19], v[82:85]
	s_waitcnt lgkmcnt(1)
	s_nop 1
	s_nop 0
	s_nop 1
	s_nop 1
	v_pk_mul_f32 v[98:99], v[92:93], v[82:83]
	v_pk_mul_f32 v[100:101], v[92:93], v[86:87]
	s_waitcnt lgkmcnt(0)
; #define SSM_SCAN_STEP(D, SQ) { _Pragma("unroll") for (int r = 0; r < 4; ++r) { \
;                     const float sr = dppf<DPP_SHR(D)>(Er[r]), si = dppf<DPP_SHR(D)>(Ei[r]); \
;                     Er[r] += mr[r] * sr - mi[r] * si; Ei[r] += mr[r] * si + mi[r] * sr; \
;                     if (SQ) { const float nr = mr[r] * mr[r] - mi[r] * mi[r], ni = 2.f * mr[r] * mi[r]; mr[r] = nr; mi[r] = ni; } } }
; template <bool PASS2>
; __device__ __forceinline__ void ssm_phase(const Params& p, const Frame& F0) {
;     ...
;             for (int i = 0; i < 4; ++i) {
;                 __builtin_amdgcn_sched_barrier(0);
;                 f32x4 Er = (f32x4){0.f, 0.f, 0.f, 0.f}, Ei = Er;
; #pragma unroll
;                 for (int ks = 0; ks < 4; ++ks) { Er = __builtin_amdgcn_mfma_f32_16x16x32_bf16(frag[(i * 4 + ks) * 64], uf[ks], Er, 0, 0, 0);
;                                                  Ei = __builtin_amdgcn_mfma_f32_16x16x32_bf16(frag[((i + 4) * 4 + ks) * 64], uf[ks], Ei, 0, 0, 0); }
;                 const f32x4 ma = m1t[8 * i], mb = m1t[8 * i + 1];
;                 float mr[4] = {ma[0], ma[2], mb[0], mb[2]}, mi[4] = {ma[1], ma[3], mb[1], mb[3]};
;                 float hr[4], hi[4];
; #pragma unroll
;                 for (int r = 0; r < 4; ++r) { hr[r] = dppf<DPP_ROR(1)>(xs[i][r]); hi[r] = dppf<DPP_ROR(1)>(xs[i + 4][r]);
;                     if (j == 0) { Er[r] += mr[r] * hr[r] - mi[r] * hi[r]; Ei[r] += mr[r] * hi[r] + mi[r] * hr[r]; } }
;     ...
;                 SSM_SCAN_STEP(1, 1) SSM_SCAN_STEP(2, 1) SSM_SCAN_STEP(4, 1) SSM_SCAN_STEP(8, 0)
;     ...
;                 xs[i] = Er; xs[i + 4] = Ei;
	v_pk_mul_f32 v[102:103], v[96:97], v[84:85]
	v_pk_mul_f32 v[112:113], v[96:97], v[88:89]
	v_pk_fma_f32 v[86:87], v[90:91], v[86:87], v[98:99] neg_lo:[0,0,1] neg_hi:[0,0,1]
	v_pk_fma_f32 v[82:83], v[90:91], v[82:83], v[100:101]
	v_pk_fma_f32 v[88:89], v[94:95], v[88:89], v[102:103] neg_lo:[0,0,1] neg_hi:[0,0,1]
	v_pk_fma_f32 v[84:85], v[94:95], v[84:85], v[112:113]
	ds_read_b128 v[90:93], v109 offset:2048
	ds_read_b128 v[94:97], v109 offset:2064
	v_add_f32_dpp v86, v86, v86 row_shr:1 row_mask:0xf bank_mask:0xf bound_ctrl:1
	v_add_f32_dpp v87, v87, v87 row_shr:1 row_mask:0xf bank_mask:0xf bound_ctrl:1
	v_add_f32_dpp v82, v82, v82 row_shr:1 row_mask:0xf bank_mask:0xf bound_ctrl:1
	v_add_f32_dpp v83, v83, v83 row_shr:1 row_mask:0xf bank_mask:0xf bound_ctrl:1
	v_add_f32_dpp v88, v88, v88 row_shr:1 row_mask:0xf bank_mask:0xf bound_ctrl:1
	v_add_f32_dpp v89, v89, v89 row_shr:1 row_mask:0xf bank_mask:0xf bound_ctrl:1
	v_add_f32_dpp v84, v84, v84 row_shr:1 row_mask:0xf bank_mask:0xf bound_ctrl:1
	v_add_f32_dpp v85, v85, v85 row_shr:1 row_mask:0xf bank_mask:0xf bound_ctrl:1
	v_add_f32_dpp v86, v86, v86 row_shr:2 row_mask:0xf bank_mask:0xf bound_ctrl:1
	v_add_f32_dpp v87, v87, v87 row_shr:2 row_mask:0xf bank_mask:0xf bound_ctrl:1
	v_add_f32_dpp v82, v82, v82 row_shr:2 row_mask:0xf bank_mask:0xf bound_ctrl:1
	v_add_f32_dpp v83, v83, v83 row_shr:2 row_mask:0xf bank_mask:0xf bound_ctrl:1
	v_add_f32_dpp v88, v88, v88 row_shr:2 row_mask:0xf bank_mask:0xf bound_ctrl:1
	v_add_f32_dpp v89, v89, v89 row_shr:2 row_mask:0xf bank_mask:0xf bound_ctrl:1
	v_add_f32_dpp v84, v84, v84 row_shr:2 row_mask:0xf bank_mask:0xf bound_ctrl:1
	v_add_f32_dpp v85, v85, v85 row_shr:2 row_mask:0xf bank_mask:0xf bound_ctrl:1
	v_add_f32_dpp v86, v86, v86 row_shr:4 row_mask:0xf bank_mask:0xf bound_ctrl:1
	v_add_f32_dpp v87, v87, v87 row_shr:4 row_mask:0xf bank_mask:0xf bound_ctrl:1
	v_add_f32_dpp v82, v82, v82 row_shr:4 row_mask:0xf bank_mask:0xf bound_ctrl:1
	v_add_f32_dpp v83, v83, v83 row_shr:4 row_mask:0xf bank_mask:0xf bound_ctrl:1
	v_add_f32_dpp v88, v88, v88 row_shr:4 row_mask:0xf bank_mask:0xf bound_ctrl:1
	v_add_f32_dpp v89, v89, v89 row_shr:4 row_mask:0xf bank_mask:0xf bound_ctrl:1
	v_add_f32_dpp v84, v84, v84 row_shr:4 row_mask:0xf bank_mask:0xf bound_ctrl:1
	v_add_f32_dpp v85, v85, v85 row_shr:4 row_mask:0xf bank_mask:0xf bound_ctrl:1
	v_add_f32_dpp v86, v86, v86 row_shr:8 row_mask:0xf bank_mask:0xf bound_ctrl:1
	v_add_f32_dpp v87, v87, v87 row_shr:8 row_mask:0xf bank_mask:0xf bound_ctrl:1
	v_add_f32_dpp v82, v82, v82 row_shr:8 row_mask:0xf bank_mask:0xf bound_ctrl:1
	v_add_f32_dpp v83, v83, v83 row_shr:8 row_mask:0xf bank_mask:0xf bound_ctrl:1
	v_add_f32_dpp v88, v88, v88 row_shr:8 row_mask:0xf bank_mask:0xf bound_ctrl:1
	v_add_f32_dpp v89, v89, v89 row_shr:8 row_mask:0xf bank_mask:0xf bound_ctrl:1
	v_add_f32_dpp v84, v84, v84 row_shr:8 row_mask:0xf bank_mask:0xf bound_ctrl:1
	v_add_f32_dpp v85, v85, v85 row_shr:8 row_mask:0xf bank_mask:0xf bound_ctrl:1
	s_waitcnt lgkmcnt(0)
	v_pk_fma_f32 v[86:87], v[90:91], v[72:73], v[86:87]
	v_pk_fma_f32 v[82:83], v[90:91], v[70:71], v[82:83]
	v_pk_fma_f32 v[88:89], v[94:95], v[76:77], v[88:89]
	v_pk_fma_f32 v[84:85], v[94:95], v[74:75], v[84:85]
	v_pk_fma_f32 v[86:87], v[92:93], v[70:71], v[86:87] neg_lo:[1,0,0] neg_hi:[1,0,0]
	v_pk_fma_f32 v[88:89], v[96:97], v[74:75], v[88:89] neg_lo:[1,0,0] neg_hi:[1,0,0]
	v_pk_fma_f32 v[70:71], v[92:93], v[72:73], v[82:83]
	v_pk_fma_f32 v[74:75], v[96:97], v[76:77], v[84:85]
	v_mov_b64_e32 v[72:73], v[86:87]
	v_mov_b64_e32 v[76:77], v[88:89]
	ds_read_b128 v[90:93], v110 offset:2688
	ds_read_b128 v[94:97], v110 offset:2704
	v_mfma_f32_16x16x32_bf16 v[32:35], v[146:149], v[28:31], 0
	v_mfma_f32_16x16x32_bf16 v[32:35], v[150:153], v[24:27], v[32:35]
	v_mfma_f32_16x16x32_bf16 v[82:85], v[212:215], v[28:31], 0
	v_mfma_f32_16x16x32_bf16 v[82:85], v[216:219], v[24:27], v[82:85]
	v_mfma_f32_16x16x32_bf16 v[32:35], v[154:157], v[20:23], v[32:35]
	v_mfma_f32_16x16x32_bf16 v[82:85], v[220:223], v[20:23], v[82:85]
	v_mfma_f32_16x16x32_bf16 v[86:89], v[158:161], v[16:19], v[32:35]
	v_mfma_f32_16x16x32_bf16 v[82:85], v[224:227], v[16:19], v[82:85]
	s_waitcnt lgkmcnt(1)
	s_nop 1
	s_nop 0
	s_nop 1
	s_nop 1
	v_pk_mul_f32 v[98:99], v[92:93], v[82:83]
	v_pk_mul_f32 v[100:101], v[92:93], v[86:87]
	s_waitcnt lgkmcnt(0)
; #define SSM_SCAN_STEP(D, SQ) { _Pragma("unroll") for (int r = 0; r < 4; ++r) { \
;                     const float sr = dppf<DPP_SHR(D)>(Er[r]), si = dppf<DPP_SHR(D)>(Ei[r]); \
;                     Er[r] += mr[r] * sr - mi[r] * si; Ei[r] += mr[r] * si + mi[r] * sr; \
;                     if (SQ) { const float nr = mr[r] * mr[r] - mi[r] * mi[r], ni = 2.f * mr[r] * mi[r]; mr[r] = nr; mi[r] = ni; } } }
; template <bool PASS2>
; __device__ __forceinline__ void ssm_phase(const Params& p, const Frame& F0) {
;     ...
;             for (int i = 0; i < 4; ++i) {
;                 __builtin_amdgcn_sched_barrier(0);
;                 f32x4 Er = (f32x4){0.f, 0.f, 0.f, 0.f}, Ei = Er;
; #pragma unroll
;                 for (int ks = 0; ks < 4; ++ks) { Er = __builtin_amdgcn_mfma_f32_16x16x32_bf16(frag[(i * 4 + ks) * 64], uf[ks], Er, 0, 0, 0);
;                                                  Ei = __builtin_amdgcn_mfma_f32_16x16x32_bf16(frag[((i + 4) * 4 + ks) * 64], uf[ks], Ei, 0, 0, 0); }
;                 const f32x4 ma = m1t[8 * i], mb = m1t[8 * i + 1];
;                 float mr[4] = {ma[0], ma[2], mb[0], mb[2]}, mi[4] = {ma[1], ma[3], mb[1], mb[3]};
;                 float hr[4], hi[4];
; #pragma unroll
;                 for (int r = 0; r < 4; ++r) { hr[r] = dppf<DPP_ROR(1)>(xs[i][r]); hi[r] = dppf<DPP_ROR(1)>(xs[i + 4][r]);
;                     if (j == 0) { Er[r] += mr[r] * hr[r] - mi[r] * hi[r]; Ei[r] += mr[r] * hi[r] + mi[r] * hr[r]; } }
;     ...
;                 SSM_SCAN_STEP(1, 1) SSM_SCAN_STEP(2, 1) SSM_SCAN_STEP(4, 1) SSM_SCAN_STEP(8, 0)
;     ...
;                 xs[i] = Er; xs[i + 4] = Ei;
	v_pk_mul_f32 v[102:103], v[96:97], v[84:85]
	v_pk_mul_f32 v[112:113], v[96:97], v[88:89]
	v_pk_fma_f32 v[86:87], v[90:91], v[86:87], v[98:99] neg_lo:[0,0,1] neg_hi:[0,0,1]
	v_pk_fma_f32 v[82:83], v[90:91], v[82:83], v[100:101]
	v_pk_fma_f32 v[88:89], v[94:95], v[88:89], v[102:103] neg_lo:[0,0,1] neg_hi:[0,0,1]
	v_pk_fma_f32 v[84:85], v[94:95], v[84:85], v[112:113]
	ds_read_b128 v[90:93], v109 offset:2176
	ds_read_b128 v[94:97], v109 offset:2192
	v_add_f32_dpp v86, v86, v86 row_shr:1 row_mask:0xf bank_mask:0xf bound_ctrl:1
	v_add_f32_dpp v87, v87, v87 row_shr:1 row_mask:0xf bank_mask:0xf bound_ctrl:1
	v_add_f32_dpp v82, v82, v82 row_shr:1 row_mask:0xf bank_mask:0xf bound_ctrl:1
	v_add_f32_dpp v83, v83, v83 row_shr:1 row_mask:0xf bank_mask:0xf bound_ctrl:1
	v_add_f32_dpp v88, v88, v88 row_shr:1 row_mask:0xf bank_mask:0xf bound_ctrl:1
	v_add_f32_dpp v89, v89, v89 row_shr:1 row_mask:0xf bank_mask:0xf bound_ctrl:1
	v_add_f32_dpp v84, v84, v84 row_shr:1 row_mask:0xf bank_mask:0xf bound_ctrl:1
	v_add_f32_dpp v85, v85, v85 row_shr:1 row_mask:0xf bank_mask:0xf bound_ctrl:1
	v_add_f32_dpp v86, v86, v86 row_shr:2 row_mask:0xf bank_mask:0xf bound_ctrl:1
	v_add_f32_dpp v87, v87, v87 row_shr:2 row_mask:0xf bank_mask:0xf bound_ctrl:1
	v_add_f32_dpp v82, v82, v82 row_shr:2 row_mask:0xf bank_mask:0xf bound_ctrl:1
	v_add_f32_dpp v83, v83, v83 row_shr:2 row_mask:0xf bank_mask:0xf bound_ctrl:1
	v_add_f32_dpp v88, v88, v88 row_shr:2 row_mask:0xf bank_mask:0xf bound_ctrl:1
	v_add_f32_dpp v89, v89, v89 row_shr:2 row_mask:0xf bank_mask:0xf bound_ctrl:1
	v_add_f32_dpp v84, v84, v84 row_shr:2 row_mask:0xf bank_mask:0xf bound_ctrl:1
	v_add_f32_dpp v85, v85, v85 row_shr:2 row_mask:0xf bank_mask:0xf bound_ctrl:1
	v_add_f32_dpp v86, v86, v86 row_shr:4 row_mask:0xf bank_mask:0xf bound_ctrl:1
	v_add_f32_dpp v87, v87, v87 row_shr:4 row_mask:0xf bank_mask:0xf bound_ctrl:1
	v_add_f32_dpp v82, v82, v82 row_shr:4 row_mask:0xf bank_mask:0xf bound_ctrl:1
	v_add_f32_dpp v83, v83, v83 row_shr:4 row_mask:0xf bank_mask:0xf bound_ctrl:1
	v_add_f32_dpp v88, v88, v88 row_shr:4 row_mask:0xf bank_mask:0xf bound_ctrl:1
	v_add_f32_dpp v89, v89, v89 row_shr:4 row_mask:0xf bank_mask:0xf bound_ctrl:1
	v_add_f32_dpp v84, v84, v84 row_shr:4 row_mask:0xf bank_mask:0xf bound_ctrl:1
	v_add_f32_dpp v85, v85, v85 row_shr:4 row_mask:0xf bank_mask:0xf bound_ctrl:1
	v_add_f32_dpp v86, v86, v86 row_shr:8 row_mask:0xf bank_mask:0xf bound_ctrl:1
	v_add_f32_dpp v87, v87, v87 row_shr:8 row_mask:0xf bank_mask:0xf bound_ctrl:1
	v_add_f32_dpp v82, v82, v82 row_shr:8 row_mask:0xf bank_mask:0xf bound_ctrl:1
	v_add_f32_dpp v83, v83, v83 row_shr:8 row_mask:0xf bank_mask:0xf bound_ctrl:1
	v_add_f32_dpp v88, v88, v88 row_shr:8 row_mask:0xf bank_mask:0xf bound_ctrl:1
	v_add_f32_dpp v89, v89, v89 row_shr:8 row_mask:0xf bank_mask:0xf bound_ctrl:1
	v_add_f32_dpp v84, v84, v84 row_shr:8 row_mask:0xf bank_mask:0xf bound_ctrl:1
	v_add_f32_dpp v85, v85, v85 row_shr:8 row_mask:0xf bank_mask:0xf bound_ctrl:1
	s_waitcnt lgkmcnt(0)
	v_pk_fma_f32 v[86:87], v[90:91], v[62:63], v[86:87]
	v_pk_fma_f32 v[82:83], v[90:91], v[60:61], v[82:83]
	v_pk_fma_f32 v[88:89], v[94:95], v[68:69], v[88:89]
	v_pk_fma_f32 v[84:85], v[94:95], v[66:67], v[84:85]
	v_pk_fma_f32 v[86:87], v[92:93], v[60:61], v[86:87] neg_lo:[1,0,0] neg_hi:[1,0,0]
	v_pk_fma_f32 v[88:89], v[96:97], v[66:67], v[88:89] neg_lo:[1,0,0] neg_hi:[1,0,0]
	v_pk_fma_f32 v[60:61], v[92:93], v[62:63], v[82:83]
	v_pk_fma_f32 v[66:67], v[96:97], v[68:69], v[84:85]
	v_mov_b64_e32 v[62:63], v[86:87]
	v_mov_b64_e32 v[68:69], v[88:89]
	ds_read_b128 v[90:93], v110 offset:2816
	ds_read_b128 v[94:97], v110 offset:2832
	v_mfma_f32_16x16x32_bf16 v[32:35], v[162:165], v[28:31], 0
	v_mfma_f32_16x16x32_bf16 v[32:35], v[166:169], v[24:27], v[32:35]
	v_mfma_f32_16x16x32_bf16 v[82:85], v[228:231], v[28:31], 0
	v_mfma_f32_16x16x32_bf16 v[82:85], v[232:235], v[24:27], v[82:85]
	v_mfma_f32_16x16x32_bf16 v[32:35], v[170:173], v[20:23], v[32:35]
	v_mfma_f32_16x16x32_bf16 v[82:85], v[236:239], v[20:23], v[82:85]
	v_mfma_f32_16x16x32_bf16 v[86:89], v[174:177], v[16:19], v[32:35]
	v_mfma_f32_16x16x32_bf16 v[82:85], v[240:243], v[16:19], v[82:85]
	s_waitcnt lgkmcnt(1)
	s_nop 1
	s_nop 0
	s_nop 1
	s_nop 1
	v_pk_mul_f32 v[98:99], v[92:93], v[82:83]
	v_pk_mul_f32 v[100:101], v[92:93], v[86:87]
	s_waitcnt lgkmcnt(0)
; #define SSM_SCAN_STEP(D, SQ) { _Pragma("unroll") for (int r = 0; r < 4; ++r) { \
;                     const float sr = dppf<DPP_SHR(D)>(Er[r]), si = dppf<DPP_SHR(D)>(Ei[r]); \
;                     Er[r] += mr[r] * sr - mi[r] * si; Ei[r] += mr[r] * si + mi[r] * sr; \
;                     if (SQ) { const float nr = mr[r] * mr[r] - mi[r] * mi[r], ni = 2.f * mr[r] * mi[r]; mr[r] = nr; mi[r] = ni; } } }
; template <bool PASS2>
; __device__ __forceinline__ void ssm_phase(const Params& p, const Frame& F0) {
;     ...
;             for (int i = 0; i < 4; ++i) {
;                 __builtin_amdgcn_sched_barrier(0);
;                 f32x4 Er = (f32x4){0.f, 0.f, 0.f, 0.f}, Ei = Er;
; #pragma unroll
;                 for (int ks = 0; ks < 4; ++ks) { Er = __builtin_amdgcn_mfma_f32_16x16x32_bf16(frag[(i * 4 + ks) * 64], uf[ks], Er, 0, 0, 0);
;                                                  Ei = __builtin_amdgcn_mfma_f32_16x16x32_bf16(frag[((i + 4) * 4 + ks) * 64], uf[ks], Ei, 0, 0, 0); }
;                 const f32x4 ma = m1t[8 * i], mb = m1t[8 * i + 1];
;                 float mr[4] = {ma[0], ma[2], mb[0], mb[2]}, mi[4] = {ma[1], ma[3], mb[1], mb[3]};
;                 float hr[4], hi[4];
; #pragma unroll
;                 for (int r = 0; r < 4; ++r) { hr[r] = dppf<DPP_ROR(1)>(xs[i][r]); hi[r] = dppf<DPP_ROR(1)>(xs[i + 4][r]);
;                     if (j == 0) { Er[r] += mr[r] * hr[r] - mi[r] * hi[r]; Ei[r] += mr[r] * hi[r] + mi[r] * hr[r]; } }
;     ...
;                 SSM_SCAN_STEP(1, 1) SSM_SCAN_STEP(2, 1) SSM_SCAN_STEP(4, 1) SSM_SCAN_STEP(8, 0)
;     ...
;                 xs[i] = Er; xs[i + 4] = Ei;
	v_pk_mul_f32 v[102:103], v[96:97], v[84:85]
	v_pk_mul_f32 v[112:113], v[96:97], v[88:89]
	v_pk_fma_f32 v[86:87], v[90:91], v[86:87], v[98:99] neg_lo:[0,0,1] neg_hi:[0,0,1]
	v_pk_fma_f32 v[82:83], v[90:91], v[82:83], v[100:101]
	v_pk_fma_f32 v[88:89], v[94:95], v[88:89], v[102:103] neg_lo:[0,0,1] neg_hi:[0,0,1]
	v_pk_fma_f32 v[84:85], v[94:95], v[84:85], v[112:113]
	ds_read_b128 v[90:93], v109 offset:2304
	ds_read_b128 v[94:97], v109 offset:2320
	v_add_f32_dpp v86, v86, v86 row_shr:1 row_mask:0xf bank_mask:0xf bound_ctrl:1
	v_add_f32_dpp v87, v87, v87 row_shr:1 row_mask:0xf bank_mask:0xf bound_ctrl:1
	v_add_f32_dpp v82, v82, v82 row_shr:1 row_mask:0xf bank_mask:0xf bound_ctrl:1
	v_add_f32_dpp v83, v83, v83 row_shr:1 row_mask:0xf bank_mask:0xf bound_ctrl:1
	v_add_f32_dpp v88, v88, v88 row_shr:1 row_mask:0xf bank_mask:0xf bound_ctrl:1
	v_add_f32_dpp v89, v89, v89 row_shr:1 row_mask:0xf bank_mask:0xf bound_ctrl:1
	v_add_f32_dpp v84, v84, v84 row_shr:1 row_mask:0xf bank_mask:0xf bound_ctrl:1
	v_add_f32_dpp v85, v85, v85 row_shr:1 row_mask:0xf bank_mask:0xf bound_ctrl:1
	v_add_f32_dpp v86, v86, v86 row_shr:2 row_mask:0xf bank_mask:0xf bound_ctrl:1
	v_add_f32_dpp v87, v87, v87 row_shr:2 row_mask:0xf bank_mask:0xf bound_ctrl:1
	v_add_f32_dpp v82, v82, v82 row_shr:2 row_mask:0xf bank_mask:0xf bound_ctrl:1
	v_add_f32_dpp v83, v83, v83 row_shr:2 row_mask:0xf bank_mask:0xf bound_ctrl:1
	v_add_f32_dpp v88, v88, v88 row_shr:2 row_mask:0xf bank_mask:0xf bound_ctrl:1
	v_add_f32_dpp v89, v89, v89 row_shr:2 row_mask:0xf bank_mask:0xf bound_ctrl:1
	v_add_f32_dpp v84, v84, v84 row_shr:2 row_mask:0xf bank_mask:0xf bound_ctrl:1
	v_add_f32_dpp v85, v85, v85 row_shr:2 row_mask:0xf bank_mask:0xf bound_ctrl:1
	v_add_f32_dpp v86, v86, v86 row_shr:4 row_mask:0xf bank_mask:0xf bound_ctrl:1
	v_add_f32_dpp v87, v87, v87 row_shr:4 row_mask:0xf bank_mask:0xf bound_ctrl:1
	v_add_f32_dpp v82, v82, v82 row_shr:4 row_mask:0xf bank_mask:0xf bound_ctrl:1
	v_add_f32_dpp v83, v83, v83 row_shr:4 row_mask:0xf bank_mask:0xf bound_ctrl:1
	v_add_f32_dpp v88, v88, v88 row_shr:4 row_mask:0xf bank_mask:0xf bound_ctrl:1
	v_add_f32_dpp v89, v89, v89 row_shr:4 row_mask:0xf bank_mask:0xf bound_ctrl:1
	v_add_f32_dpp v84, v84, v84 row_shr:4 row_mask:0xf bank_mask:0xf bound_ctrl:1
	v_add_f32_dpp v85, v85, v85 row_shr:4 row_mask:0xf bank_mask:0xf bound_ctrl:1
	v_add_f32_dpp v86, v86, v86 row_shr:8 row_mask:0xf bank_mask:0xf bound_ctrl:1
	v_add_f32_dpp v87, v87, v87 row_shr:8 row_mask:0xf bank_mask:0xf bound_ctrl:1
	v_add_f32_dpp v82, v82, v82 row_shr:8 row_mask:0xf bank_mask:0xf bound_ctrl:1
	v_add_f32_dpp v83, v83, v83 row_shr:8 row_mask:0xf bank_mask:0xf bound_ctrl:1
	v_add_f32_dpp v88, v88, v88 row_shr:8 row_mask:0xf bank_mask:0xf bound_ctrl:1
	v_add_f32_dpp v89, v89, v89 row_shr:8 row_mask:0xf bank_mask:0xf bound_ctrl:1
	v_add_f32_dpp v84, v84, v84 row_shr:8 row_mask:0xf bank_mask:0xf bound_ctrl:1
	v_add_f32_dpp v85, v85, v85 row_shr:8 row_mask:0xf bank_mask:0xf bound_ctrl:1
	s_waitcnt lgkmcnt(0)
	v_pk_fma_f32 v[86:87], v[90:91], v[54:55], v[86:87]
	v_pk_fma_f32 v[82:83], v[90:91], v[52:53], v[82:83]
	v_pk_fma_f32 v[88:89], v[94:95], v[58:59], v[88:89]
	v_pk_fma_f32 v[84:85], v[94:95], v[56:57], v[84:85]
	v_pk_fma_f32 v[86:87], v[92:93], v[52:53], v[86:87] neg_lo:[1,0,0] neg_hi:[1,0,0]
	v_pk_fma_f32 v[88:89], v[96:97], v[56:57], v[88:89] neg_lo:[1,0,0] neg_hi:[1,0,0]
	v_pk_fma_f32 v[52:53], v[92:93], v[54:55], v[82:83]
	v_pk_fma_f32 v[56:57], v[96:97], v[58:59], v[84:85]
	v_mov_b64_e32 v[54:55], v[86:87]
	v_mov_b64_e32 v[58:59], v[88:89]
	ds_read_b128 v[90:93], v110 offset:2944
	ds_read_b128 v[94:97], v110 offset:2960
	v_mfma_f32_16x16x32_bf16 v[32:35], v[178:181], v[28:31], 0
	v_mfma_f32_16x16x32_bf16 v[28:31], v[244:247], v[28:31], 0
	v_mfma_f32_16x16x32_bf16 v[32:35], v[182:185], v[24:27], v[32:35]
	v_mfma_f32_16x16x32_bf16 v[24:27], v[248:251], v[24:27], v[28:31]
	v_mfma_f32_16x16x32_bf16 v[28:31], v[186:189], v[20:23], v[32:35]
	v_mfma_f32_16x16x32_bf16 v[20:23], v[114:117], v[20:23], v[24:27]
	s_nop 0
	s_nop 0
	v_mfma_f32_16x16x32_bf16 v[24:27], v[190:193], v[16:19], v[28:31]
	v_mfma_f32_16x16x32_bf16 v[20:23], v[118:121], v[16:19], v[20:23]
	s_waitcnt lgkmcnt(1)
	s_nop 2
	s_nop 3
	v_pk_mul_f32 v[98:99], v[92:93], v[20:21]
	s_nop 1
	v_pk_mul_f32 v[100:101], v[92:93], v[24:25]
	s_waitcnt lgkmcnt(0)
; __device__ __forceinline__ unsigned cvt_pk_bf16(float lo, float hi) { unsigned r; asm("v_cvt_pk_bf16_f32 %0, %1, %2" : "=v"(r) : "v"(lo), "v"(hi)); return r; }
; #define SSM_SCAN_STEP(D, SQ) { _Pragma("unroll") for (int r = 0; r < 4; ++r) { \
;                     const float sr = dppf<DPP_SHR(D)>(Er[r]), si = dppf<DPP_SHR(D)>(Ei[r]); \
;                     Er[r] += mr[r] * sr - mi[r] * si; Ei[r] += mr[r] * si + mi[r] * sr; \
;                     if (SQ) { const float nr = mr[r] * mr[r] - mi[r] * mi[r], ni = 2.f * mr[r] * mi[r]; mr[r] = nr; mi[r] = ni; } } }
; template <bool PASS2>
; __device__ __forceinline__ void ssm_phase(const Params& p, const Frame& F0) {
;     ...
;         for (int cc = 0; cc < nch; ++cc) {
;     ...
;             for (int i = 0; i < 4; ++i) {
;                 __builtin_amdgcn_sched_barrier(0);
;                 f32x4 Er = (f32x4){0.f, 0.f, 0.f, 0.f}, Ei = Er;
; #pragma unroll
;                 for (int ks = 0; ks < 4; ++ks) { Er = __builtin_amdgcn_mfma_f32_16x16x32_bf16(frag[(i * 4 + ks) * 64], uf[ks], Er, 0, 0, 0);
;                                                  Ei = __builtin_amdgcn_mfma_f32_16x16x32_bf16(frag[((i + 4) * 4 + ks) * 64], uf[ks], Ei, 0, 0, 0); }
;                 const f32x4 ma = m1t[8 * i], mb = m1t[8 * i + 1];
;                 float mr[4] = {ma[0], ma[2], mb[0], mb[2]}, mi[4] = {ma[1], ma[3], mb[1], mb[3]};
;                 float hr[4], hi[4];
; #pragma unroll
;                 for (int r = 0; r < 4; ++r) { hr[r] = dppf<DPP_ROR(1)>(xs[i][r]); hi[r] = dppf<DPP_ROR(1)>(xs[i + 4][r]);
;                     if (j == 0) { Er[r] += mr[r] * hr[r] - mi[r] * hi[r]; Ei[r] += mr[r] * hi[r] + mi[r] * hr[r]; } }
;     ...
;                 SSM_SCAN_STEP(1, 1) SSM_SCAN_STEP(2, 1) SSM_SCAN_STEP(4, 1) SSM_SCAN_STEP(8, 0)
;     ...
;                 if constexpr (PASS2) {
;                     float vr[4], vi[4];
; #pragma unroll
;                     for (int r = 0; r < 4; ++r) { const float pr_ = dppf<DPP_ROR(1)>(Er[r]), pi_ = dppf<DPP_ROR(1)>(Ei[r]); vr[r] = (j == 0) ? hr[r] : pr_; vi[r] = (j == 0) ? hi[r] : pi_; }
;                     hw[i >> 1][2 * (i & 1)] = cvt_pk_bf16(vr[0], vr[1]); hw[i >> 1][2 * (i & 1) + 1] = cvt_pk_bf16(vr[2], vr[3]);
;                     hw[2 + (i >> 1)][2 * (i & 1)] = cvt_pk_bf16(vi[0], vi[1]); hw[2 + (i >> 1)][2 * (i & 1) + 1] = cvt_pk_bf16(vi[2], vi[3]);
;                 }
;                 xs[i] = Er; xs[i + 4] = Ei;
	v_pk_mul_f32 v[102:103], v[96:97], v[22:23]
	v_pk_mul_f32 v[112:113], v[96:97], v[26:27]
	v_pk_fma_f32 v[24:25], v[90:91], v[24:25], v[98:99] neg_lo:[0,0,1] neg_hi:[0,0,1]
	v_pk_fma_f32 v[20:21], v[90:91], v[20:21], v[100:101]
	v_pk_fma_f32 v[26:27], v[94:95], v[26:27], v[102:103] neg_lo:[0,0,1] neg_hi:[0,0,1]
	v_pk_fma_f32 v[22:23], v[94:95], v[22:23], v[112:113]
	ds_read_b128 v[90:93], v109 offset:2432
	ds_read_b128 v[94:97], v109 offset:2448
	v_add_f32_dpp v24, v24, v24 row_shr:1 row_mask:0xf bank_mask:0xf bound_ctrl:1
	v_add_f32_dpp v25, v25, v25 row_shr:1 row_mask:0xf bank_mask:0xf bound_ctrl:1
	v_add_f32_dpp v20, v20, v20 row_shr:1 row_mask:0xf bank_mask:0xf bound_ctrl:1
	v_add_f32_dpp v21, v21, v21 row_shr:1 row_mask:0xf bank_mask:0xf bound_ctrl:1
	v_add_f32_dpp v26, v26, v26 row_shr:1 row_mask:0xf bank_mask:0xf bound_ctrl:1
	v_add_f32_dpp v27, v27, v27 row_shr:1 row_mask:0xf bank_mask:0xf bound_ctrl:1
	v_add_f32_dpp v22, v22, v22 row_shr:1 row_mask:0xf bank_mask:0xf bound_ctrl:1
	v_add_f32_dpp v23, v23, v23 row_shr:1 row_mask:0xf bank_mask:0xf bound_ctrl:1
	v_add_f32_dpp v24, v24, v24 row_shr:2 row_mask:0xf bank_mask:0xf bound_ctrl:1
	v_add_f32_dpp v25, v25, v25 row_shr:2 row_mask:0xf bank_mask:0xf bound_ctrl:1
	v_add_f32_dpp v20, v20, v20 row_shr:2 row_mask:0xf bank_mask:0xf bound_ctrl:1
	v_add_f32_dpp v21, v21, v21 row_shr:2 row_mask:0xf bank_mask:0xf bound_ctrl:1
	v_add_f32_dpp v26, v26, v26 row_shr:2 row_mask:0xf bank_mask:0xf bound_ctrl:1
	v_add_f32_dpp v27, v27, v27 row_shr:2 row_mask:0xf bank_mask:0xf bound_ctrl:1
	v_add_f32_dpp v22, v22, v22 row_shr:2 row_mask:0xf bank_mask:0xf bound_ctrl:1
	v_add_f32_dpp v23, v23, v23 row_shr:2 row_mask:0xf bank_mask:0xf bound_ctrl:1
	v_add_f32_dpp v24, v24, v24 row_shr:4 row_mask:0xf bank_mask:0xf bound_ctrl:1
	v_add_f32_dpp v25, v25, v25 row_shr:4 row_mask:0xf bank_mask:0xf bound_ctrl:1
	v_add_f32_dpp v20, v20, v20 row_shr:4 row_mask:0xf bank_mask:0xf bound_ctrl:1
	v_add_f32_dpp v21, v21, v21 row_shr:4 row_mask:0xf bank_mask:0xf bound_ctrl:1
	v_add_f32_dpp v26, v26, v26 row_shr:4 row_mask:0xf bank_mask:0xf bound_ctrl:1
	v_add_f32_dpp v27, v27, v27 row_shr:4 row_mask:0xf bank_mask:0xf bound_ctrl:1
	v_add_f32_dpp v22, v22, v22 row_shr:4 row_mask:0xf bank_mask:0xf bound_ctrl:1
	v_add_f32_dpp v23, v23, v23 row_shr:4 row_mask:0xf bank_mask:0xf bound_ctrl:1
	v_add_f32_dpp v24, v24, v24 row_shr:8 row_mask:0xf bank_mask:0xf bound_ctrl:1
	v_add_f32_dpp v25, v25, v25 row_shr:8 row_mask:0xf bank_mask:0xf bound_ctrl:1
	v_add_f32_dpp v20, v20, v20 row_shr:8 row_mask:0xf bank_mask:0xf bound_ctrl:1
	v_add_f32_dpp v21, v21, v21 row_shr:8 row_mask:0xf bank_mask:0xf bound_ctrl:1
	v_add_f32_dpp v26, v26, v26 row_shr:8 row_mask:0xf bank_mask:0xf bound_ctrl:1
	v_add_f32_dpp v27, v27, v27 row_shr:8 row_mask:0xf bank_mask:0xf bound_ctrl:1
	v_add_f32_dpp v22, v22, v22 row_shr:8 row_mask:0xf bank_mask:0xf bound_ctrl:1
	v_add_f32_dpp v23, v23, v23 row_shr:8 row_mask:0xf bank_mask:0xf bound_ctrl:1
	s_waitcnt lgkmcnt(0)
	v_pk_fma_f32 v[24:25], v[90:91], v[46:47], v[24:25]
	v_pk_fma_f32 v[20:21], v[90:91], v[44:45], v[20:21]
	v_pk_fma_f32 v[26:27], v[94:95], v[50:51], v[26:27]
	v_pk_fma_f32 v[22:23], v[94:95], v[48:49], v[22:23]
	v_pk_fma_f32 v[24:25], v[92:93], v[44:45], v[24:25] neg_lo:[1,0,0] neg_hi:[1,0,0]
	v_pk_fma_f32 v[26:27], v[96:97], v[48:49], v[26:27] neg_lo:[1,0,0] neg_hi:[1,0,0]
	v_pk_fma_f32 v[44:45], v[92:93], v[46:47], v[20:21]
	v_pk_fma_f32 v[48:49], v[96:97], v[50:51], v[22:23]
	v_mov_b64_e32 v[46:47], v[24:25]
	v_mov_b64_e32 v[50:51], v[26:27]
	s_addk_i32 s0, 0x80
	s_cmpk_eq_i32 s0, 0x180
	s_cbranch_scc0 .LBB0_527
	ds_read_b128 v[16:19], v105
	ds_read_b128 v[20:23], v105 offset:1024
	ds_read_b128 v[24:27], v105 offset:16384
	ds_read_b128 v[28:31], v105 offset:17408
	v_mov_b32_dpp v65, v72 row_ror:1 row_mask:0xf bank_mask:0xf bound_ctrl:1
	v_mov_b32_dpp v64, v70 row_ror:1 row_mask:0xf bank_mask:0xf bound_ctrl:1
	s_waitcnt vmcnt(3)
	s_waitcnt lgkmcnt(3)
	v_mfma_f32_16x16x32_bf16 v[16:19], v[16:19], v[12:15], 0
	s_waitcnt vmcnt(2)
	s_waitcnt lgkmcnt(2)
	v_mfma_f32_16x16x32_bf16 v[16:19], v[20:23], v[4:7], v[16:19]
	ds_read_b128 v[20:23], v105 offset:2048
	s_waitcnt lgkmcnt(2)
	v_mfma_f32_16x16x32_bf16 v[24:27], v[24:27], v[12:15], 0
	s_waitcnt lgkmcnt(1)
	v_mfma_f32_16x16x32_bf16 v[24:27], v[28:31], v[4:7], v[24:27]
	ds_read_b128 v[28:31], v105 offset:18432
	ds_read_b128 v[32:35], v105 offset:3072
	ds_read_b128 v[78:81], v105 offset:19456
	s_waitcnt vmcnt(1)
	s_waitcnt lgkmcnt(3)
	v_mfma_f32_16x16x32_bf16 v[16:19], v[20:23], v[8:11], v[16:19]
	ds_read_b128 v[20:23], v109
	ds_read_b128 v[82:85], v109 offset:16
	s_waitcnt lgkmcnt(1)
	v_mov_b32_e32 v72, v21
	v_mfma_f32_16x16x32_bf16 v[24:27], v[28:31], v[8:11], v[24:27]
	v_mul_f32_e64 v28, v20, v65
	v_mul_f32_e64 v29, v21, v64
	v_mov_b32_e32 v70, v20
	v_sub_f32_e32 v28, v28, v29
	s_waitcnt vmcnt(0)
	v_mfma_f32_16x16x32_bf16 v[16:19], v[32:35], v[0:3], v[16:19]
	v_mfma_f32_16x16x32_bf16 v[24:27], v[78:81], v[0:3], v[24:27]
	s_nop 6
	v_add_f32_e32 v32, v16, v28
	v_pk_mul_f32 v[28:29], v[20:21], v[64:65]
	ds_read_b64 v[20:21], v109 offset:512
	v_cndmask_b32_e64 v16, v16, v32, s[6:7]
	v_add_f32_e32 v28, v29, v28
	v_add_f32_e32 v33, v24, v28
	v_mov_b32_dpp v29, v73 row_ror:1 row_mask:0xf bank_mask:0xf bound_ctrl:1
	v_mov_b32_dpp v28, v71 row_ror:1 row_mask:0xf bank_mask:0xf bound_ctrl:1
	v_pk_mul_f32 v[30:31], v[22:23], v[28:29] op_sel:[0,1] op_sel_hi:[1,0]
	v_pk_mul_f32 v[28:29], v[22:23], v[28:29]
	v_sub_f32_e32 v30, v30, v31
	v_add_f32_e32 v28, v29, v28
	v_add_f32_e32 v35, v28, v25
	v_mov_b32_dpp v29, v76 row_ror:1 row_mask:0xf bank_mask:0xf bound_ctrl:1
	v_mov_b32_dpp v28, v74 row_ror:1 row_mask:0xf bank_mask:0xf bound_ctrl:1
	v_add_f32_e32 v34, v30, v17
	s_waitcnt lgkmcnt(1)
; #define SSM_SCAN_STEP(D, SQ) { _Pragma("unroll") for (int r = 0; r < 4; ++r) { \
;                     const float sr = dppf<DPP_SHR(D)>(Er[r]), si = dppf<DPP_SHR(D)>(Ei[r]); \
;                     Er[r] += mr[r] * sr - mi[r] * si; Ei[r] += mr[r] * si + mi[r] * sr; \
;                     if (SQ) { const float nr = mr[r] * mr[r] - mi[r] * mi[r], ni = 2.f * mr[r] * mi[r]; mr[r] = nr; mi[r] = ni; } } }
; template <bool PASS2>
; __device__ __forceinline__ void ssm_phase(const Params& p, const Frame& F0) {
;     ...
;                 for (int r = 0; r < 4; ++r) { hr[r] = dppf<DPP_ROR(1)>(xs[i][r]); hi[r] = dppf<DPP_ROR(1)>(xs[i + 4][r]);
;                     if (j == 0) { Er[r] += mr[r] * hr[r] - mi[r] * hi[r]; Ei[r] += mr[r] * hi[r] + mi[r] * hr[r]; } }
;     ...
;                 SSM_SCAN_STEP(1, 1) SSM_SCAN_STEP(2, 1) SSM_SCAN_STEP(4, 1) SSM_SCAN_STEP(8, 0)
	v_pk_mul_f32 v[30:31], v[82:83], v[28:29] op_sel:[0,1] op_sel_hi:[1,0]
	v_pk_mul_f32 v[28:29], v[82:83], v[28:29]
	v_sub_f32_e32 v30, v30, v31
	v_add_f32_e32 v28, v29, v28
	v_add_f32_e32 v65, v28, v26
	v_mov_b32_dpp v29, v77 row_ror:1 row_mask:0xf bank_mask:0xf bound_ctrl:1
	v_mov_b32_dpp v28, v75 row_ror:1 row_mask:0xf bank_mask:0xf bound_ctrl:1
	v_add_f32_e32 v64, v30, v18
	v_pk_mul_f32 v[30:31], v[84:85], v[28:29] op_sel:[0,1] op_sel_hi:[1,0]
	v_pk_mul_f32 v[28:29], v[84:85], v[28:29]
	v_sub_f32_e32 v30, v30, v31
	v_add_f32_e32 v28, v29, v28
	v_cndmask_b32_e64 v25, v25, v35, s[6:7]
	v_cndmask_b32_e64 v24, v24, v33, s[6:7]
	v_add_f32_e32 v30, v30, v19
	v_add_f32_e32 v28, v28, v27
	v_cndmask_b32_e64 v17, v17, v34, s[6:7]
	v_mov_b32_dpp v32, v24 row_shr:1 row_mask:0xf bank_mask:0xf bound_ctrl:1
	v_mov_b32_dpp v33, v25 row_shr:1 row_mask:0xf bank_mask:0xf bound_ctrl:1
	v_mov_b32_e32 v73, v23
	v_cndmask_b32_e64 v29, v27, v28, s[6:7]
	v_cndmask_b32_e64 v28, v26, v65, s[6:7]
	v_cndmask_b32_e64 v27, v19, v30, s[6:7]
	v_cndmask_b32_e64 v26, v18, v64, s[6:7]
	v_mov_b32_dpp v30, v16 row_shr:1 row_mask:0xf bank_mask:0xf bound_ctrl:1
	v_mov_b32_dpp v31, v17 row_shr:1 row_mask:0xf bank_mask:0xf bound_ctrl:1
	v_mov_b32_e32 v71, v22
	ds_read_b64 v[22:23], v109 offset:520
	v_pk_mul_f32 v[18:19], v[72:73], v[32:33]
	v_pk_mul_f32 v[32:33], v[70:71], v[32:33]
	v_pk_fma_f32 v[18:19], v[70:71], v[30:31], v[18:19] neg_lo:[0,0,1] neg_hi:[0,0,1]
	v_pk_fma_f32 v[30:31], v[72:73], v[30:31], v[32:33]
	v_pk_add_f32 v[74:75], v[18:19], v[16:17]
	ds_read_b128 v[16:19], v109 offset:1024
	v_pk_add_f32 v[24:25], v[30:31], v[24:25]
	v_mov_b32_dpp v76, v74 row_shr:2 row_mask:0xf bank_mask:0xf bound_ctrl:1
	s_nop 0
	v_mov_b32_dpp v30, v24 row_shr:2 row_mask:0xf bank_mask:0xf bound_ctrl:1
	v_mov_b32_dpp v31, v25 row_shr:2 row_mask:0xf bank_mask:0xf bound_ctrl:1
	v_mov_b32_dpp v77, v75 row_shr:2 row_mask:0xf bank_mask:0xf bound_ctrl:1
	s_waitcnt lgkmcnt(1)
	v_pk_mul_f32 v[32:33], v[22:23], v[30:31]
	v_pk_fma_f32 v[32:33], v[20:21], v[76:77], v[32:33] neg_lo:[0,0,1] neg_hi:[0,0,1]
	v_pk_mul_f32 v[20:21], v[20:21], v[30:31]
	v_pk_fma_f32 v[20:21], v[22:23], v[76:77], v[20:21]
	v_pk_add_f32 v[32:33], v[32:33], v[74:75]
	ds_read_b128 v[72:75], v109 offset:528
	v_pk_add_f32 v[22:23], v[24:25], v[20:21]
	v_mov_b32_dpp v64, v28 row_shr:1 row_mask:0xf bank_mask:0xf bound_ctrl:1
	v_mov_b32_dpp v24, v32 row_shr:4 row_mask:0xf bank_mask:0xf bound_ctrl:1
	v_mov_b32_dpp v30, v22 row_shr:4 row_mask:0xf bank_mask:0xf bound_ctrl:1
	v_mov_b32_dpp v31, v23 row_shr:4 row_mask:0xf bank_mask:0xf bound_ctrl:1
	v_mov_b32_dpp v25, v33 row_shr:4 row_mask:0xf bank_mask:0xf bound_ctrl:1
	s_waitcnt lgkmcnt(1)
	v_pk_mul_f32 v[20:21], v[18:19], v[30:31]
	v_pk_mul_f32 v[30:31], v[16:17], v[30:31]
	v_pk_fma_f32 v[20:21], v[16:17], v[24:25], v[20:21] neg_lo:[0,0,1] neg_hi:[0,0,1]
	v_mov_b32_dpp v65, v29 row_shr:1 row_mask:0xf bank_mask:0xf bound_ctrl:1
	v_pk_add_f32 v[20:21], v[32:33], v[20:21]
	v_pk_fma_f32 v[24:25], v[18:19], v[24:25], v[30:31]
	v_mov_b32_e32 v32, v83
	v_mov_b32_e32 v33, v85
	v_mov_b32_dpp v34, v26 row_shr:1 row_mask:0xf bank_mask:0xf bound_ctrl:1
	v_mov_b32_dpp v35, v27 row_shr:1 row_mask:0xf bank_mask:0xf bound_ctrl:1
	v_pk_add_f32 v[22:23], v[22:23], v[24:25]
	v_mov_b32_e32 v30, v82
	v_mov_b32_e32 v31, v84
	v_pk_mul_f32 v[24:25], v[32:33], v[64:65]
	s_nop 0
	v_pk_fma_f32 v[24:25], v[30:31], v[34:35], v[24:25] neg_lo:[0,0,1] neg_hi:[0,0,1]
	s_nop 0
	v_pk_add_f32 v[70:71], v[24:25], v[26:27]
	ds_read_b128 v[24:27], v109 offset:1040
	v_pk_mul_f32 v[30:31], v[30:31], v[64:65]
	v_pk_fma_f32 v[30:31], v[32:33], v[34:35], v[30:31]
	v_mov_b32_dpp v76, v70 row_shr:2 row_mask:0xf bank_mask:0xf bound_ctrl:1
	v_pk_add_f32 v[28:29], v[30:31], v[28:29]
	v_mov_b32_dpp v77, v71 row_shr:2 row_mask:0xf bank_mask:0xf bound_ctrl:1
	s_nop 0
	v_mov_b32_dpp v30, v28 row_shr:2 row_mask:0xf bank_mask:0xf bound_ctrl:1
	v_mov_b32_dpp v31, v29 row_shr:2 row_mask:0xf bank_mask:0xf bound_ctrl:1
	s_waitcnt lgkmcnt(1)
	v_pk_mul_f32 v[32:33], v[74:75], v[30:31]
	v_pk_mul_f32 v[30:31], v[72:73], v[30:31]
	v_pk_fma_f32 v[32:33], v[72:73], v[76:77], v[32:33] neg_lo:[0,0,1] neg_hi:[0,0,1]
	v_pk_fma_f32 v[30:31], v[74:75], v[76:77], v[30:31]
	v_pk_add_f32 v[30:31], v[28:29], v[30:31]
	v_pk_add_f32 v[32:33], v[70:71], v[32:33]
	s_nop 0
	v_mov_b32_dpp v64, v30 row_shr:4 row_mask:0xf bank_mask:0xf bound_ctrl:1
	v_mov_b32_dpp v65, v31 row_shr:4 row_mask:0xf bank_mask:0xf bound_ctrl:1
	v_mov_b32_dpp v34, v32 row_shr:4 row_mask:0xf bank_mask:0xf bound_ctrl:1
	v_mov_b32_dpp v35, v33 row_shr:4 row_mask:0xf bank_mask:0xf bound_ctrl:1
	s_waitcnt lgkmcnt(0)
	v_pk_mul_f32 v[28:29], v[26:27], v[64:65]
	s_nop 0
	v_pk_fma_f32 v[28:29], v[24:25], v[34:35], v[28:29] neg_lo:[0,0,1] neg_hi:[0,0,1]
	s_nop 0
	v_pk_add_f32 v[28:29], v[32:33], v[28:29]
	v_pk_mul_f32 v[32:33], v[24:25], v[64:65]
	v_mov_b32_dpp v64, v22 row_shr:8 row_mask:0xf bank_mask:0xf bound_ctrl:1
	v_pk_fma_f32 v[32:33], v[26:27], v[34:35], v[32:33]
	v_mov_b32_dpp v65, v23 row_shr:8 row_mask:0xf bank_mask:0xf bound_ctrl:1
	v_pk_add_f32 v[32:33], v[30:31], v[32:33]
	v_mov_b32_dpp v30, v20 row_shr:8 row_mask:0xf bank_mask:0xf bound_ctrl:1
	v_mov_b32_dpp v31, v21 row_shr:8 row_mask:0xf bank_mask:0xf bound_ctrl:1
	v_mov_b32_dpp v34, v28 row_shr:8 row_mask:0xf bank_mask:0xf bound_ctrl:1
	v_mov_b32_dpp v70, v32 row_shr:8 row_mask:0xf bank_mask:0xf bound_ctrl:1
	v_mov_b32_dpp v35, v29 row_shr:8 row_mask:0xf bank_mask:0xf bound_ctrl:1
	v_mov_b32_dpp v71, v33 row_shr:8 row_mask:0xf bank_mask:0xf bound_ctrl:1
	ds_read_b128 v[72:75], v105 offset:4096
	ds_read_b128 v[76:79], v105 offset:5120
	ds_read_b128 v[80:83], v105 offset:20480
	ds_read_b128 v[84:87], v105 offset:21504
	v_mov_b32_dpp v101, v62 row_ror:1 row_mask:0xf bank_mask:0xf bound_ctrl:1
	v_mov_b32_dpp v100, v60 row_ror:1 row_mask:0xf bank_mask:0xf bound_ctrl:1
	s_waitcnt lgkmcnt(3)
; #define SSM_SCAN_STEP(D, SQ) { _Pragma("unroll") for (int r = 0; r < 4; ++r) { \
;                     const float sr = dppf<DPP_SHR(D)>(Er[r]), si = dppf<DPP_SHR(D)>(Ei[r]); \
;                     Er[r] += mr[r] * sr - mi[r] * si; Ei[r] += mr[r] * si + mi[r] * sr; \
;                     if (SQ) { const float nr = mr[r] * mr[r] - mi[r] * mi[r], ni = 2.f * mr[r] * mi[r]; mr[r] = nr; mi[r] = ni; } } }
; template <bool PASS2>
; __device__ __forceinline__ void ssm_phase(const Params& p, const Frame& F0) {
;     ...
;                 for (int ks = 0; ks < 4; ++ks) { Er = __builtin_amdgcn_mfma_f32_16x16x32_bf16(frag[(i * 4 + ks) * 64], uf[ks], Er, 0, 0, 0);
;                                                  Ei = __builtin_amdgcn_mfma_f32_16x16x32_bf16(frag[((i + 4) * 4 + ks) * 64], uf[ks], Ei, 0, 0, 0); }
;                 const f32x4 ma = m1t[8 * i], mb = m1t[8 * i + 1];
;                 float mr[4] = {ma[0], ma[2], mb[0], mb[2]}, mi[4] = {ma[1], ma[3], mb[1], mb[3]};
;                 float hr[4], hi[4];
; #pragma unroll
;                 for (int r = 0; r < 4; ++r) { hr[r] = dppf<DPP_ROR(1)>(xs[i][r]); hi[r] = dppf<DPP_ROR(1)>(xs[i + 4][r]);
;                     if (j == 0) { Er[r] += mr[r] * hr[r] - mi[r] * hi[r]; Ei[r] += mr[r] * hi[r] + mi[r] * hr[r]; } }
;     ...
;                 SSM_SCAN_STEP(1, 1) SSM_SCAN_STEP(2, 1) SSM_SCAN_STEP(4, 1) SSM_SCAN_STEP(8, 0)
	v_mfma_f32_16x16x32_bf16 v[72:75], v[72:75], v[12:15], 0
	v_mov_b32_dpp v63, v63 row_ror:1 row_mask:0xf bank_mask:0xf bound_ctrl:1
	v_mov_b32_dpp v62, v61 row_ror:1 row_mask:0xf bank_mask:0xf bound_ctrl:1
	s_waitcnt lgkmcnt(2)
	v_mfma_f32_16x16x32_bf16 v[72:75], v[76:79], v[4:7], v[72:75]
	ds_read_b128 v[76:79], v105 offset:6144
	s_waitcnt lgkmcnt(2)
	v_mfma_f32_16x16x32_bf16 v[80:83], v[80:83], v[12:15], 0
	s_waitcnt lgkmcnt(1)
	v_mfma_f32_16x16x32_bf16 v[80:83], v[84:87], v[4:7], v[80:83]
	ds_read_b128 v[84:87], v105 offset:22528
	ds_read_b128 v[88:91], v105 offset:7168
	ds_read_b128 v[92:95], v105 offset:23552
	s_waitcnt lgkmcnt(3)
	v_mfma_f32_16x16x32_bf16 v[72:75], v[76:79], v[8:11], v[72:75]
	ds_read_b128 v[76:79], v109 offset:128
	ds_read_b128 v[96:99], v109 offset:144
	s_waitcnt lgkmcnt(4)
	v_mfma_f32_16x16x32_bf16 v[80:83], v[84:87], v[8:11], v[80:83]
	s_waitcnt lgkmcnt(1)
	v_pk_mul_f32 v[84:85], v[76:77], v[100:101] op_sel:[0,1] op_sel_hi:[1,0]
	s_nop 0
	v_sub_f32_e32 v60, v84, v85
	v_mfma_f32_16x16x32_bf16 v[72:75], v[88:91], v[0:3], v[72:75]
	v_mul_f32_e64 v84, v76, v100
	v_mul_f32_e64 v85, v77, v101
	v_mov_b32_e32 v88, v77
	v_mov_b32_e32 v89, v79
	v_mfma_f32_16x16x32_bf16 v[80:83], v[92:95], v[0:3], v[80:83]
	s_nop 2
	v_add_f32_e32 v86, v72, v60
	v_add_f32_e32 v60, v85, v84
	s_nop 2
	v_add_f32_e32 v84, v80, v60
	v_pk_mul_f32 v[60:61], v[78:79], v[62:63] op_sel:[0,1] op_sel_hi:[1,0]
	s_nop 0
	v_sub_f32_e32 v60, v60, v61
	v_add_f32_e32 v85, v60, v73
	v_pk_mul_f32 v[60:61], v[78:79], v[62:63]
	s_nop 0
	v_add_f32_e32 v60, v61, v60
	v_add_f32_e32 v87, v60, v81
	v_mov_b32_dpp v61, v68 row_ror:1 row_mask:0xf bank_mask:0xf bound_ctrl:1
	v_mov_b32_dpp v60, v66 row_ror:1 row_mask:0xf bank_mask:0xf bound_ctrl:1
	s_waitcnt lgkmcnt(0)
	v_pk_mul_f32 v[62:63], v[96:97], v[60:61] op_sel:[0,1] op_sel_hi:[1,0]
	v_pk_mul_f32 v[60:61], v[96:97], v[60:61]
	v_sub_f32_e32 v62, v62, v63
	v_add_f32_e32 v60, v61, v60
	v_add_f32_e32 v66, v60, v82
	v_mov_b32_dpp v61, v69 row_ror:1 row_mask:0xf bank_mask:0xf bound_ctrl:1
	v_mov_b32_dpp v60, v67 row_ror:1 row_mask:0xf bank_mask:0xf bound_ctrl:1
	v_add_f32_e32 v68, v62, v74
	v_pk_mul_f32 v[62:63], v[98:99], v[60:61] op_sel:[0,1] op_sel_hi:[1,0]
	v_pk_mul_f32 v[60:61], v[98:99], v[60:61]
	v_sub_f32_e32 v62, v62, v63
	v_add_f32_e32 v60, v61, v60
	v_add_f32_e32 v60, v60, v83
	v_cndmask_b32_e64 v82, v82, v66, s[6:7]
	v_cndmask_b32_e64 v67, v81, v87, s[6:7]
	v_cndmask_b32_e64 v66, v80, v84, s[6:7]
	v_add_f32_e32 v62, v62, v75
	v_cndmask_b32_e64 v83, v83, v60, s[6:7]
	v_cndmask_b32_e64 v61, v73, v85, s[6:7]
	v_cndmask_b32_e64 v60, v72, v86, s[6:7]
	v_mov_b32_dpp v72, v66 row_shr:1 row_mask:0xf bank_mask:0xf bound_ctrl:1
	v_mov_b32_dpp v73, v67 row_shr:1 row_mask:0xf bank_mask:0xf bound_ctrl:1
	v_cndmask_b32_e64 v75, v75, v62, s[6:7]
	v_cndmask_b32_e64 v74, v74, v68, s[6:7]
	v_mov_b32_dpp v68, v60 row_shr:1 row_mask:0xf bank_mask:0xf bound_ctrl:1
	v_mov_b32_dpp v69, v61 row_shr:1 row_mask:0xf bank_mask:0xf bound_ctrl:1
	v_mov_b32_e32 v86, v76
	v_mov_b32_e32 v87, v78
	ds_read_b128 v[76:79], v109 offset:640
	v_pk_mul_f32 v[62:63], v[88:89], v[72:73]
	v_pk_mul_f32 v[72:73], v[86:87], v[72:73]
	v_pk_fma_f32 v[62:63], v[86:87], v[68:69], v[62:63] neg_lo:[0,0,1] neg_hi:[0,0,1]
	v_pk_fma_f32 v[68:69], v[88:89], v[68:69], v[72:73]
	v_pk_add_f32 v[90:91], v[62:63], v[60:61]
	ds_read_b128 v[60:63], v109 offset:1152
	v_pk_add_f32 v[66:67], v[68:69], v[66:67]
	v_mov_b32_dpp v92, v90 row_shr:2 row_mask:0xf bank_mask:0xf bound_ctrl:1
	s_nop 0
	v_mov_b32_dpp v68, v66 row_shr:2 row_mask:0xf bank_mask:0xf bound_ctrl:1
	v_mov_b32_dpp v69, v67 row_shr:2 row_mask:0xf bank_mask:0xf bound_ctrl:1
	v_mov_b32_dpp v93, v91 row_shr:2 row_mask:0xf bank_mask:0xf bound_ctrl:1
	s_waitcnt lgkmcnt(1)
	v_pk_mul_f32 v[72:73], v[78:79], v[68:69]
	v_pk_mul_f32 v[68:69], v[76:77], v[68:69]
	v_pk_fma_f32 v[68:69], v[78:79], v[92:93], v[68:69]
	v_pk_fma_f32 v[72:73], v[76:77], v[92:93], v[72:73] neg_lo:[0,0,1] neg_hi:[0,0,1]
	v_pk_add_f32 v[68:69], v[66:67], v[68:69]
	v_pk_add_f32 v[72:73], v[72:73], v[90:91]
	ds_read_b128 v[88:91], v109 offset:656
	v_mov_b32_dpp v78, v68 row_shr:4 row_mask:0xf bank_mask:0xf bound_ctrl:1
	v_mov_b32_dpp v79, v69 row_shr:4 row_mask:0xf bank_mask:0xf bound_ctrl:1
	v_mov_b32_dpp v76, v72 row_shr:4 row_mask:0xf bank_mask:0xf bound_ctrl:1
	v_mov_b32_dpp v77, v73 row_shr:4 row_mask:0xf bank_mask:0xf bound_ctrl:1
	s_waitcnt lgkmcnt(1)
	v_pk_mul_f32 v[66:67], v[62:63], v[78:79]
	v_mov_b32_dpp v84, v82 row_shr:1 row_mask:0xf bank_mask:0xf bound_ctrl:1
	v_pk_fma_f32 v[66:67], v[60:61], v[76:77], v[66:67] neg_lo:[0,0,1] neg_hi:[0,0,1]
	v_mov_b32_dpp v85, v83 row_shr:1 row_mask:0xf bank_mask:0xf bound_ctrl:1
	v_pk_add_f32 v[66:67], v[72:73], v[66:67]
	v_pk_mul_f32 v[72:73], v[60:61], v[78:79]
	v_mov_b32_e32 v78, v97
	v_pk_fma_f32 v[72:73], v[62:63], v[76:77], v[72:73]
	v_mov_b32_e32 v79, v99
	v_mov_b32_dpp v80, v74 row_shr:1 row_mask:0xf bank_mask:0xf bound_ctrl:1
	v_mov_b32_dpp v81, v75 row_shr:1 row_mask:0xf bank_mask:0xf bound_ctrl:1
	v_pk_add_f32 v[68:69], v[68:69], v[72:73]
	v_mov_b32_e32 v76, v96
	v_mov_b32_e32 v77, v98
	v_pk_mul_f32 v[72:73], v[78:79], v[84:85]
	s_nop 0
	v_pk_fma_f32 v[72:73], v[76:77], v[80:81], v[72:73] neg_lo:[0,0,1] neg_hi:[0,0,1]
	s_nop 0
	v_pk_add_f32 v[86:87], v[72:73], v[74:75]
	ds_read_b128 v[72:75], v109 offset:1168
	v_pk_mul_f32 v[76:77], v[76:77], v[84:85]
	v_pk_fma_f32 v[76:77], v[78:79], v[80:81], v[76:77]
	v_mov_b32_dpp v92, v86 row_shr:2 row_mask:0xf bank_mask:0xf bound_ctrl:1
	v_pk_add_f32 v[76:77], v[76:77], v[82:83]
	v_mov_b32_dpp v93, v87 row_shr:2 row_mask:0xf bank_mask:0xf bound_ctrl:1
	s_nop 0
	v_mov_b32_dpp v78, v76 row_shr:2 row_mask:0xf bank_mask:0xf bound_ctrl:1
	v_mov_b32_dpp v79, v77 row_shr:2 row_mask:0xf bank_mask:0xf bound_ctrl:1
	s_waitcnt lgkmcnt(1)
; #define SSM_SCAN_STEP(D, SQ) { _Pragma("unroll") for (int r = 0; r < 4; ++r) { \
;                     const float sr = dppf<DPP_SHR(D)>(Er[r]), si = dppf<DPP_SHR(D)>(Ei[r]); \
;                     Er[r] += mr[r] * sr - mi[r] * si; Ei[r] += mr[r] * si + mi[r] * sr; \
;                     if (SQ) { const float nr = mr[r] * mr[r] - mi[r] * mi[r], ni = 2.f * mr[r] * mi[r]; mr[r] = nr; mi[r] = ni; } } }
; template <bool PASS2>
; __device__ __forceinline__ void ssm_phase(const Params& p, const Frame& F0) {
;     ...
;                 for (int ks = 0; ks < 4; ++ks) { Er = __builtin_amdgcn_mfma_f32_16x16x32_bf16(frag[(i * 4 + ks) * 64], uf[ks], Er, 0, 0, 0);
;                                                  Ei = __builtin_amdgcn_mfma_f32_16x16x32_bf16(frag[((i + 4) * 4 + ks) * 64], uf[ks], Ei, 0, 0, 0); }
;                 const f32x4 ma = m1t[8 * i], mb = m1t[8 * i + 1];
;                 float mr[4] = {ma[0], ma[2], mb[0], mb[2]}, mi[4] = {ma[1], ma[3], mb[1], mb[3]};
;                 float hr[4], hi[4];
; #pragma unroll
;                 for (int r = 0; r < 4; ++r) { hr[r] = dppf<DPP_ROR(1)>(xs[i][r]); hi[r] = dppf<DPP_ROR(1)>(xs[i + 4][r]);
;                     if (j == 0) { Er[r] += mr[r] * hr[r] - mi[r] * hi[r]; Ei[r] += mr[r] * hi[r] + mi[r] * hr[r]; } }
;     ...
;                 SSM_SCAN_STEP(1, 1) SSM_SCAN_STEP(2, 1) SSM_SCAN_STEP(4, 1) SSM_SCAN_STEP(8, 0)
	v_pk_mul_f32 v[80:81], v[90:91], v[78:79]
	v_pk_mul_f32 v[78:79], v[88:89], v[78:79]
	v_pk_fma_f32 v[80:81], v[88:89], v[92:93], v[80:81] neg_lo:[0,0,1] neg_hi:[0,0,1]
	v_pk_fma_f32 v[78:79], v[90:91], v[92:93], v[78:79]
	v_pk_add_f32 v[78:79], v[76:77], v[78:79]
	v_pk_add_f32 v[80:81], v[86:87], v[80:81]
	s_nop 0
	v_mov_b32_dpp v84, v78 row_shr:4 row_mask:0xf bank_mask:0xf bound_ctrl:1
	v_mov_b32_dpp v85, v79 row_shr:4 row_mask:0xf bank_mask:0xf bound_ctrl:1
	v_mov_b32_dpp v82, v80 row_shr:4 row_mask:0xf bank_mask:0xf bound_ctrl:1
	v_mov_b32_dpp v83, v81 row_shr:4 row_mask:0xf bank_mask:0xf bound_ctrl:1
	s_waitcnt lgkmcnt(0)
	v_pk_mul_f32 v[76:77], v[74:75], v[84:85]
	s_nop 0
	v_pk_fma_f32 v[76:77], v[72:73], v[82:83], v[76:77] neg_lo:[0,0,1] neg_hi:[0,0,1]
	s_nop 0
	v_pk_add_f32 v[76:77], v[80:81], v[76:77]
	v_pk_mul_f32 v[80:81], v[72:73], v[84:85]
	v_mov_b32_dpp v84, v68 row_shr:8 row_mask:0xf bank_mask:0xf bound_ctrl:1
	v_pk_fma_f32 v[80:81], v[74:75], v[82:83], v[80:81]
	v_mov_b32_dpp v85, v69 row_shr:8 row_mask:0xf bank_mask:0xf bound_ctrl:1
	v_pk_add_f32 v[80:81], v[78:79], v[80:81]
	v_mov_b32_dpp v78, v66 row_shr:8 row_mask:0xf bank_mask:0xf bound_ctrl:1
	v_mov_b32_dpp v79, v67 row_shr:8 row_mask:0xf bank_mask:0xf bound_ctrl:1
	v_mov_b32_dpp v82, v76 row_shr:8 row_mask:0xf bank_mask:0xf bound_ctrl:1
	v_mov_b32_dpp v86, v80 row_shr:8 row_mask:0xf bank_mask:0xf bound_ctrl:1
	v_mov_b32_dpp v83, v77 row_shr:8 row_mask:0xf bank_mask:0xf bound_ctrl:1
	v_mov_b32_dpp v87, v81 row_shr:8 row_mask:0xf bank_mask:0xf bound_ctrl:1
	ds_read_b128 v[88:91], v105 offset:8192
	ds_read_b128 v[92:95], v105 offset:9216
	ds_read_b128 v[96:99], v105 offset:24576
	ds_read_b128 v[100:103], v105 offset:25600
	v_mov_b32_dpp v123, v54 row_ror:1 row_mask:0xf bank_mask:0xf bound_ctrl:1
	v_mov_b32_dpp v122, v52 row_ror:1 row_mask:0xf bank_mask:0xf bound_ctrl:1
	s_waitcnt lgkmcnt(3)
	v_mfma_f32_16x16x32_bf16 v[88:91], v[88:91], v[12:15], 0
	v_mov_b32_dpp v55, v55 row_ror:1 row_mask:0xf bank_mask:0xf bound_ctrl:1
	v_mov_b32_dpp v54, v53 row_ror:1 row_mask:0xf bank_mask:0xf bound_ctrl:1
	s_waitcnt lgkmcnt(2)
	v_mfma_f32_16x16x32_bf16 v[88:91], v[92:95], v[4:7], v[88:91]
	ds_read_b128 v[92:95], v105 offset:10240
	s_waitcnt lgkmcnt(2)
	v_mfma_f32_16x16x32_bf16 v[96:99], v[96:99], v[12:15], 0
	s_waitcnt lgkmcnt(1)
	v_mfma_f32_16x16x32_bf16 v[96:99], v[100:103], v[4:7], v[96:99]
	ds_read_b128 v[100:103], v105 offset:26624
	ds_read_b128 v[110:113], v105 offset:11264
	ds_read_b128 v[114:117], v105 offset:27648
	s_waitcnt lgkmcnt(3)
	v_mfma_f32_16x16x32_bf16 v[88:91], v[92:95], v[8:11], v[88:91]
	ds_read_b128 v[92:95], v109 offset:256
	ds_read_b128 v[118:121], v109 offset:272
	s_waitcnt lgkmcnt(4)
	v_mfma_f32_16x16x32_bf16 v[96:99], v[100:103], v[8:11], v[96:99]
	s_waitcnt lgkmcnt(1)
	v_pk_mul_f32 v[100:101], v[92:93], v[122:123] op_sel:[0,1] op_sel_hi:[1,0]
	s_nop 0
	v_sub_f32_e32 v52, v100, v101
	v_mfma_f32_16x16x32_bf16 v[88:91], v[110:113], v[0:3], v[88:91]
	v_mul_f32_e64 v100, v92, v122
	v_mul_f32_e64 v101, v93, v123
	v_mov_b32_e32 v110, v93
	v_mov_b32_e32 v111, v95
	v_mfma_f32_16x16x32_bf16 v[96:99], v[114:117], v[0:3], v[96:99]
	s_nop 2
	v_add_f32_e32 v102, v88, v52
	v_add_f32_e32 v52, v101, v100
	s_nop 2
	v_add_f32_e32 v100, v96, v52
	v_pk_mul_f32 v[52:53], v[94:95], v[54:55] op_sel:[0,1] op_sel_hi:[1,0]
	s_nop 0
	v_sub_f32_e32 v52, v52, v53
	v_add_f32_e32 v101, v52, v89
	v_pk_mul_f32 v[52:53], v[94:95], v[54:55]
	s_nop 0
	v_add_f32_e32 v52, v53, v52
	v_add_f32_e32 v103, v52, v97
	v_mov_b32_dpp v53, v58 row_ror:1 row_mask:0xf bank_mask:0xf bound_ctrl:1
	v_mov_b32_dpp v52, v56 row_ror:1 row_mask:0xf bank_mask:0xf bound_ctrl:1
	s_waitcnt lgkmcnt(0)
	v_pk_mul_f32 v[54:55], v[118:119], v[52:53] op_sel:[0,1] op_sel_hi:[1,0]
	v_pk_mul_f32 v[52:53], v[118:119], v[52:53]
	v_sub_f32_e32 v54, v54, v55
	v_add_f32_e32 v52, v53, v52
	v_add_f32_e32 v56, v52, v98
	v_mov_b32_dpp v53, v59 row_ror:1 row_mask:0xf bank_mask:0xf bound_ctrl:1
	v_mov_b32_dpp v52, v57 row_ror:1 row_mask:0xf bank_mask:0xf bound_ctrl:1
	v_add_f32_e32 v58, v54, v90
	v_pk_mul_f32 v[54:55], v[120:121], v[52:53] op_sel:[0,1] op_sel_hi:[1,0]
	v_pk_mul_f32 v[52:53], v[120:121], v[52:53]
	v_sub_f32_e32 v54, v54, v55
	v_add_f32_e32 v52, v53, v52
	v_add_f32_e32 v52, v52, v99
	v_cndmask_b32_e64 v98, v98, v56, s[6:7]
	v_cndmask_b32_e64 v57, v97, v103, s[6:7]
	v_cndmask_b32_e64 v56, v96, v100, s[6:7]
	v_add_f32_e32 v54, v54, v91
	v_cndmask_b32_e64 v99, v99, v52, s[6:7]
	v_cndmask_b32_e64 v53, v89, v101, s[6:7]
	v_cndmask_b32_e64 v52, v88, v102, s[6:7]
	v_mov_b32_dpp v88, v56 row_shr:1 row_mask:0xf bank_mask:0xf bound_ctrl:1
	v_mov_b32_dpp v89, v57 row_shr:1 row_mask:0xf bank_mask:0xf bound_ctrl:1
	v_cndmask_b32_e64 v91, v91, v54, s[6:7]
	v_cndmask_b32_e64 v90, v90, v58, s[6:7]
	v_mov_b32_dpp v58, v52 row_shr:1 row_mask:0xf bank_mask:0xf bound_ctrl:1
	v_mov_b32_dpp v59, v53 row_shr:1 row_mask:0xf bank_mask:0xf bound_ctrl:1
	v_mov_b32_e32 v102, v92
	v_mov_b32_e32 v103, v94
	ds_read_b128 v[92:95], v109 offset:768
	v_pk_mul_f32 v[54:55], v[110:111], v[88:89]
	v_pk_mul_f32 v[88:89], v[102:103], v[88:89]
	v_pk_fma_f32 v[54:55], v[102:103], v[58:59], v[54:55] neg_lo:[0,0,1] neg_hi:[0,0,1]
	v_pk_fma_f32 v[58:59], v[110:111], v[58:59], v[88:89]
	v_pk_add_f32 v[112:113], v[54:55], v[52:53]
	ds_read_b128 v[52:55], v109 offset:1280
	v_pk_add_f32 v[56:57], v[58:59], v[56:57]
	v_mov_b32_dpp v114, v112 row_shr:2 row_mask:0xf bank_mask:0xf bound_ctrl:1
	s_nop 0
	v_mov_b32_dpp v58, v56 row_shr:2 row_mask:0xf bank_mask:0xf bound_ctrl:1
	v_mov_b32_dpp v59, v57 row_shr:2 row_mask:0xf bank_mask:0xf bound_ctrl:1
	v_mov_b32_dpp v115, v113 row_shr:2 row_mask:0xf bank_mask:0xf bound_ctrl:1
	s_waitcnt lgkmcnt(1)
; #define SSM_SCAN_STEP(D, SQ) { _Pragma("unroll") for (int r = 0; r < 4; ++r) { \
;                     const float sr = dppf<DPP_SHR(D)>(Er[r]), si = dppf<DPP_SHR(D)>(Ei[r]); \
;                     Er[r] += mr[r] * sr - mi[r] * si; Ei[r] += mr[r] * si + mi[r] * sr; \
;                     if (SQ) { const float nr = mr[r] * mr[r] - mi[r] * mi[r], ni = 2.f * mr[r] * mi[r]; mr[r] = nr; mi[r] = ni; } } }
; template <bool PASS2>
; __device__ __forceinline__ void ssm_phase(const Params& p, const Frame& F0) {
;     ...
;                 for (int ks = 0; ks < 4; ++ks) { Er = __builtin_amdgcn_mfma_f32_16x16x32_bf16(frag[(i * 4 + ks) * 64], uf[ks], Er, 0, 0, 0);
;                                                  Ei = __builtin_amdgcn_mfma_f32_16x16x32_bf16(frag[((i + 4) * 4 + ks) * 64], uf[ks], Ei, 0, 0, 0); }
;                 const f32x4 ma = m1t[8 * i], mb = m1t[8 * i + 1];
;                 float mr[4] = {ma[0], ma[2], mb[0], mb[2]}, mi[4] = {ma[1], ma[3], mb[1], mb[3]};
;                 float hr[4], hi[4];
; #pragma unroll
;                 for (int r = 0; r < 4; ++r) { hr[r] = dppf<DPP_ROR(1)>(xs[i][r]); hi[r] = dppf<DPP_ROR(1)>(xs[i + 4][r]);
;                     if (j == 0) { Er[r] += mr[r] * hr[r] - mi[r] * hi[r]; Ei[r] += mr[r] * hi[r] + mi[r] * hr[r]; } }
;     ...
;                 SSM_SCAN_STEP(1, 1) SSM_SCAN_STEP(2, 1) SSM_SCAN_STEP(4, 1) SSM_SCAN_STEP(8, 0)
	v_pk_mul_f32 v[88:89], v[94:95], v[58:59]
	v_pk_mul_f32 v[58:59], v[92:93], v[58:59]
	v_pk_fma_f32 v[58:59], v[94:95], v[114:115], v[58:59]
	v_pk_fma_f32 v[88:89], v[92:93], v[114:115], v[88:89] neg_lo:[0,0,1] neg_hi:[0,0,1]
	v_pk_add_f32 v[58:59], v[56:57], v[58:59]
	v_pk_add_f32 v[88:89], v[88:89], v[112:113]
	ds_read_b128 v[110:113], v109 offset:784
	v_mov_b32_dpp v94, v58 row_shr:4 row_mask:0xf bank_mask:0xf bound_ctrl:1
	v_mov_b32_dpp v95, v59 row_shr:4 row_mask:0xf bank_mask:0xf bound_ctrl:1
	v_mov_b32_dpp v92, v88 row_shr:4 row_mask:0xf bank_mask:0xf bound_ctrl:1
	v_mov_b32_dpp v93, v89 row_shr:4 row_mask:0xf bank_mask:0xf bound_ctrl:1
	s_waitcnt lgkmcnt(1)
	v_pk_mul_f32 v[56:57], v[54:55], v[94:95]
	v_mov_b32_dpp v100, v98 row_shr:1 row_mask:0xf bank_mask:0xf bound_ctrl:1
	v_pk_fma_f32 v[56:57], v[52:53], v[92:93], v[56:57] neg_lo:[0,0,1] neg_hi:[0,0,1]
	v_mov_b32_dpp v101, v99 row_shr:1 row_mask:0xf bank_mask:0xf bound_ctrl:1
	v_pk_add_f32 v[56:57], v[88:89], v[56:57]
	v_pk_mul_f32 v[88:89], v[52:53], v[94:95]
	v_mov_b32_e32 v94, v119
	v_pk_fma_f32 v[88:89], v[54:55], v[92:93], v[88:89]
	v_mov_b32_e32 v95, v121
	v_mov_b32_dpp v96, v90 row_shr:1 row_mask:0xf bank_mask:0xf bound_ctrl:1
	v_mov_b32_dpp v97, v91 row_shr:1 row_mask:0xf bank_mask:0xf bound_ctrl:1
	v_pk_add_f32 v[58:59], v[58:59], v[88:89]
	v_mov_b32_e32 v92, v118
	v_mov_b32_e32 v93, v120
	v_pk_mul_f32 v[88:89], v[94:95], v[100:101]
	s_nop 0
	v_pk_fma_f32 v[88:89], v[92:93], v[96:97], v[88:89] neg_lo:[0,0,1] neg_hi:[0,0,1]
	s_nop 0
	v_pk_add_f32 v[102:103], v[88:89], v[90:91]
	ds_read_b128 v[88:91], v109 offset:1296
	v_pk_mul_f32 v[92:93], v[92:93], v[100:101]
	v_pk_fma_f32 v[92:93], v[94:95], v[96:97], v[92:93]
	v_mov_b32_dpp v114, v102 row_shr:2 row_mask:0xf bank_mask:0xf bound_ctrl:1
	v_pk_add_f32 v[92:93], v[92:93], v[98:99]
	v_mov_b32_dpp v115, v103 row_shr:2 row_mask:0xf bank_mask:0xf bound_ctrl:1
	s_nop 0
	v_mov_b32_dpp v94, v92 row_shr:2 row_mask:0xf bank_mask:0xf bound_ctrl:1
	v_mov_b32_dpp v95, v93 row_shr:2 row_mask:0xf bank_mask:0xf bound_ctrl:1
	s_waitcnt lgkmcnt(1)
	v_pk_mul_f32 v[96:97], v[112:113], v[94:95]
	v_pk_mul_f32 v[94:95], v[110:111], v[94:95]
	v_pk_fma_f32 v[96:97], v[110:111], v[114:115], v[96:97] neg_lo:[0,0,1] neg_hi:[0,0,1]
	v_pk_fma_f32 v[94:95], v[112:113], v[114:115], v[94:95]
	v_pk_add_f32 v[94:95], v[92:93], v[94:95]
	v_pk_add_f32 v[96:97], v[102:103], v[96:97]
	s_nop 0
	v_mov_b32_dpp v100, v94 row_shr:4 row_mask:0xf bank_mask:0xf bound_ctrl:1
	v_mov_b32_dpp v101, v95 row_shr:4 row_mask:0xf bank_mask:0xf bound_ctrl:1
	v_mov_b32_dpp v98, v96 row_shr:4 row_mask:0xf bank_mask:0xf bound_ctrl:1
	v_mov_b32_dpp v99, v97 row_shr:4 row_mask:0xf bank_mask:0xf bound_ctrl:1
	s_waitcnt lgkmcnt(0)
	v_pk_mul_f32 v[92:93], v[90:91], v[100:101]
	s_nop 0
	v_pk_fma_f32 v[92:93], v[88:89], v[98:99], v[92:93] neg_lo:[0,0,1] neg_hi:[0,0,1]
	s_nop 0
	v_pk_add_f32 v[92:93], v[96:97], v[92:93]
	v_pk_mul_f32 v[96:97], v[88:89], v[100:101]
	v_mov_b32_dpp v100, v58 row_shr:8 row_mask:0xf bank_mask:0xf bound_ctrl:1
	v_pk_fma_f32 v[96:97], v[90:91], v[98:99], v[96:97]
	v_mov_b32_dpp v101, v59 row_shr:8 row_mask:0xf bank_mask:0xf bound_ctrl:1
	v_pk_add_f32 v[96:97], v[94:95], v[96:97]
	v_mov_b32_dpp v94, v56 row_shr:8 row_mask:0xf bank_mask:0xf bound_ctrl:1
	v_mov_b32_dpp v95, v57 row_shr:8 row_mask:0xf bank_mask:0xf bound_ctrl:1
	v_mov_b32_dpp v98, v92 row_shr:8 row_mask:0xf bank_mask:0xf bound_ctrl:1
	v_mov_b32_dpp v102, v96 row_shr:8 row_mask:0xf bank_mask:0xf bound_ctrl:1
	v_mov_b32_dpp v99, v93 row_shr:8 row_mask:0xf bank_mask:0xf bound_ctrl:1
	v_mov_b32_dpp v103, v97 row_shr:8 row_mask:0xf bank_mask:0xf bound_ctrl:1
	ds_read_b128 v[110:113], v105 offset:12288
	ds_read_b128 v[114:117], v105 offset:28672
	v_mov_b32_dpp v47, v47 row_ror:1 row_mask:0xf bank_mask:0xf bound_ctrl:1
	s_waitcnt lgkmcnt(1)
	v_mfma_f32_16x16x32_bf16 v[110:113], v[110:113], v[12:15], 0
	s_waitcnt lgkmcnt(0)
	v_mfma_f32_16x16x32_bf16 v[12:15], v[114:117], v[12:15], 0
	ds_read_b128 v[114:117], v105 offset:13312
	s_waitcnt lgkmcnt(0)
	v_mfma_f32_16x16x32_bf16 v[110:113], v[114:117], v[4:7], v[110:113]
	ds_read_b128 v[114:117], v105 offset:29696
	s_waitcnt lgkmcnt(0)
	v_mfma_f32_16x16x32_bf16 v[4:7], v[114:117], v[4:7], v[12:15]
	s_nop 2
	ds_read_b128 v[12:15], v105 offset:14336
	s_waitcnt lgkmcnt(0)
	v_mfma_f32_16x16x32_bf16 v[12:15], v[12:15], v[8:11], v[110:113]
	s_nop 2
	ds_read_b128 v[110:113], v105 offset:30720
	s_waitcnt lgkmcnt(0)
	v_mfma_f32_16x16x32_bf16 v[4:7], v[110:113], v[8:11], v[4:7]
	ds_read_b128 v[8:11], v105 offset:15360
	v_mov_b32_dpp v111, v46 row_ror:1 row_mask:0xf bank_mask:0xf bound_ctrl:1
	v_mov_b32_dpp v110, v44 row_ror:1 row_mask:0xf bank_mask:0xf bound_ctrl:1
	s_waitcnt lgkmcnt(0)
	v_mfma_f32_16x16x32_bf16 v[8:11], v[8:11], v[0:3], v[12:15]
	s_nop 2
	ds_read_b128 v[12:15], v105 offset:31744
	v_mov_b32_dpp v46, v45 row_ror:1 row_mask:0xf bank_mask:0xf bound_ctrl:1
	s_waitcnt lgkmcnt(0)
	v_mfma_f32_16x16x32_bf16 v[0:3], v[12:15], v[0:3], v[4:7]
	s_nop 2
	ds_read_b128 v[4:7], v109 offset:384
	ds_read_b128 v[12:15], v109 offset:400
	s_waitcnt lgkmcnt(1)
	v_pk_mul_f32 v[112:113], v[4:5], v[110:111] op_sel:[0,1] op_sel_hi:[1,0]
	s_nop 0
	v_sub_f32_e32 v44, v112, v113
	v_pk_mul_f32 v[110:111], v[4:5], v[110:111]
	v_add_f32_e32 v112, v8, v44
	v_add_f32_e32 v44, v111, v110
	v_add_f32_e32 v110, v0, v44
	v_pk_mul_f32 v[44:45], v[6:7], v[46:47] op_sel:[0,1] op_sel_hi:[1,0]
	v_mov_b32_e32 v114, v5
	v_sub_f32_e32 v44, v44, v45
	v_add_f32_e32 v111, v44, v9
	v_pk_mul_f32 v[44:45], v[6:7], v[46:47]
	v_mov_b32_e32 v115, v7
	v_add_f32_e32 v44, v45, v44
	v_add_f32_e32 v113, v44, v1
	v_mov_b32_dpp v45, v50 row_ror:1 row_mask:0xf bank_mask:0xf bound_ctrl:1
	v_mov_b32_dpp v44, v48 row_ror:1 row_mask:0xf bank_mask:0xf bound_ctrl:1
	s_waitcnt lgkmcnt(0)
; #define SSM_SCAN_STEP(D, SQ) { _Pragma("unroll") for (int r = 0; r < 4; ++r) { \
;                     const float sr = dppf<DPP_SHR(D)>(Er[r]), si = dppf<DPP_SHR(D)>(Ei[r]); \
;                     Er[r] += mr[r] * sr - mi[r] * si; Ei[r] += mr[r] * si + mi[r] * sr; \
;                     if (SQ) { const float nr = mr[r] * mr[r] - mi[r] * mi[r], ni = 2.f * mr[r] * mi[r]; mr[r] = nr; mi[r] = ni; } } }
; template <bool PASS2>
; __device__ __forceinline__ void ssm_phase(const Params& p, const Frame& F0) {
;     ...
;                 for (int r = 0; r < 4; ++r) { hr[r] = dppf<DPP_ROR(1)>(xs[i][r]); hi[r] = dppf<DPP_ROR(1)>(xs[i + 4][r]);
;                     if (j == 0) { Er[r] += mr[r] * hr[r] - mi[r] * hi[r]; Ei[r] += mr[r] * hi[r] + mi[r] * hr[r]; } }
;     ...
;                 SSM_SCAN_STEP(1, 1) SSM_SCAN_STEP(2, 1) SSM_SCAN_STEP(4, 1) SSM_SCAN_STEP(8, 0)
;     ...
;         if constexpr (!PASS2) { if (j == 15) { float* wb = Wst + (size_t)((g * 2 + b) * 32 + wch) * 128;
; #pragma unroll
;                 for (int i = 0; i < 4; ++i) { *(f32x4*)(wb + 16 * i + 4 * gq) = xs[i]; *(f32x4*)(wb + 64 + 16 * i + 4 * gq) = xs[i + 4]; } } }
	v_pk_mul_f32 v[46:47], v[12:13], v[44:45] op_sel:[0,1] op_sel_hi:[1,0]
	v_pk_mul_f32 v[44:45], v[12:13], v[44:45]
	v_sub_f32_e32 v46, v46, v47
	v_add_f32_e32 v44, v45, v44
	v_add_f32_e32 v50, v44, v2
	v_mov_b32_dpp v45, v51 row_ror:1 row_mask:0xf bank_mask:0xf bound_ctrl:1
	v_mov_b32_dpp v44, v49 row_ror:1 row_mask:0xf bank_mask:0xf bound_ctrl:1
	v_add_f32_e32 v48, v46, v10
	v_pk_mul_f32 v[46:47], v[14:15], v[44:45] op_sel:[0,1] op_sel_hi:[1,0]
	v_pk_mul_f32 v[44:45], v[14:15], v[44:45]
	v_sub_f32_e32 v46, v46, v47
	v_add_f32_e32 v49, v46, v11
	v_add_f32_e32 v44, v45, v44
	v_cndmask_b32_e64 v47, v1, v113, s[6:7]
	v_cndmask_b32_e64 v46, v0, v110, s[6:7]
	v_add_f32_e32 v44, v44, v3
	v_cndmask_b32_e64 v11, v11, v49, s[6:7]
	v_cndmask_b32_e64 v10, v10, v48, s[6:7]
	v_cndmask_b32_e64 v1, v9, v111, s[6:7]
	v_cndmask_b32_e64 v0, v8, v112, s[6:7]
	v_mov_b32_dpp v48, v46 row_shr:1 row_mask:0xf bank_mask:0xf bound_ctrl:1
	v_mov_b32_dpp v49, v47 row_shr:1 row_mask:0xf bank_mask:0xf bound_ctrl:1
	v_cndmask_b32_e64 v45, v3, v44, s[6:7]
	v_cndmask_b32_e64 v44, v2, v50, s[6:7]
	v_mov_b32_dpp v8, v0 row_shr:1 row_mask:0xf bank_mask:0xf bound_ctrl:1
	v_mov_b32_dpp v9, v1 row_shr:1 row_mask:0xf bank_mask:0xf bound_ctrl:1
	v_mov_b32_e32 v112, v4
	ds_read_b64 v[4:5], v109 offset:896
	v_mov_b32_e32 v113, v6
	ds_read_b64 v[6:7], v109 offset:904
	v_pk_mul_f32 v[2:3], v[114:115], v[48:49]
	v_pk_mul_f32 v[48:49], v[112:113], v[48:49]
	v_pk_fma_f32 v[2:3], v[112:113], v[8:9], v[2:3] neg_lo:[0,0,1] neg_hi:[0,0,1]
	v_pk_fma_f32 v[8:9], v[114:115], v[8:9], v[48:49]
	v_pk_add_f32 v[116:117], v[2:3], v[0:1]
	ds_read_b128 v[0:3], v109 offset:1408
	v_pk_add_f32 v[8:9], v[8:9], v[46:47]
	v_mov_b32_dpp v118, v116 row_shr:2 row_mask:0xf bank_mask:0xf bound_ctrl:1
	s_nop 0
	v_mov_b32_dpp v46, v8 row_shr:2 row_mask:0xf bank_mask:0xf bound_ctrl:1
	v_mov_b32_dpp v47, v9 row_shr:2 row_mask:0xf bank_mask:0xf bound_ctrl:1
	v_mov_b32_dpp v119, v117 row_shr:2 row_mask:0xf bank_mask:0xf bound_ctrl:1
	s_waitcnt lgkmcnt(1)
	v_pk_mul_f32 v[48:49], v[6:7], v[46:47]
	v_pk_fma_f32 v[48:49], v[4:5], v[118:119], v[48:49] neg_lo:[0,0,1] neg_hi:[0,0,1]
	v_pk_mul_f32 v[4:5], v[4:5], v[46:47]
	v_pk_fma_f32 v[4:5], v[6:7], v[118:119], v[4:5]
	v_pk_add_f32 v[48:49], v[48:49], v[116:117]
	v_pk_add_f32 v[6:7], v[8:9], v[4:5]
	v_mov_b32_dpp v110, v44 row_shr:1 row_mask:0xf bank_mask:0xf bound_ctrl:1
	v_mov_b32_dpp v8, v48 row_shr:4 row_mask:0xf bank_mask:0xf bound_ctrl:1
	v_mov_b32_dpp v46, v6 row_shr:4 row_mask:0xf bank_mask:0xf bound_ctrl:1
	v_mov_b32_dpp v47, v7 row_shr:4 row_mask:0xf bank_mask:0xf bound_ctrl:1
	v_mov_b32_dpp v9, v49 row_shr:4 row_mask:0xf bank_mask:0xf bound_ctrl:1
	s_waitcnt lgkmcnt(0)
	v_pk_mul_f32 v[4:5], v[2:3], v[46:47]
	v_pk_mul_f32 v[46:47], v[0:1], v[46:47]
	v_pk_fma_f32 v[4:5], v[0:1], v[8:9], v[4:5] neg_lo:[0,0,1] neg_hi:[0,0,1]
	v_mov_b32_dpp v111, v45 row_shr:1 row_mask:0xf bank_mask:0xf bound_ctrl:1
	v_pk_add_f32 v[4:5], v[48:49], v[4:5]
	v_pk_fma_f32 v[8:9], v[2:3], v[8:9], v[46:47]
	v_mov_b32_e32 v48, v13
	v_mov_b32_e32 v49, v15
	v_mov_b32_dpp v50, v10 row_shr:1 row_mask:0xf bank_mask:0xf bound_ctrl:1
	v_mov_b32_dpp v51, v11 row_shr:1 row_mask:0xf bank_mask:0xf bound_ctrl:1
	v_pk_add_f32 v[6:7], v[6:7], v[8:9]
	v_mov_b32_e32 v46, v12
	ds_read_b64 v[12:13], v109 offset:912
	v_mov_b32_e32 v47, v14
	ds_read_b64 v[14:15], v109 offset:920
	v_pk_mul_f32 v[8:9], v[48:49], v[110:111]
	s_nop 0
	v_pk_fma_f32 v[8:9], v[46:47], v[50:51], v[8:9] neg_lo:[0,0,1] neg_hi:[0,0,1]
	s_nop 0
	v_pk_add_f32 v[112:113], v[8:9], v[10:11]
	ds_read_b128 v[8:11], v109 offset:1424
	v_pk_mul_f32 v[46:47], v[46:47], v[110:111]
	v_pk_fma_f32 v[46:47], v[48:49], v[50:51], v[46:47]
	v_mov_b32_dpp v114, v112 row_shr:2 row_mask:0xf bank_mask:0xf bound_ctrl:1
	v_pk_add_f32 v[44:45], v[46:47], v[44:45]
	v_mov_b32_dpp v115, v113 row_shr:2 row_mask:0xf bank_mask:0xf bound_ctrl:1
	s_nop 0
	v_mov_b32_dpp v46, v44 row_shr:2 row_mask:0xf bank_mask:0xf bound_ctrl:1
	v_mov_b32_dpp v47, v45 row_shr:2 row_mask:0xf bank_mask:0xf bound_ctrl:1
	s_waitcnt lgkmcnt(1)
	v_pk_mul_f32 v[48:49], v[14:15], v[46:47]
	v_pk_fma_f32 v[48:49], v[12:13], v[114:115], v[48:49] neg_lo:[0,0,1] neg_hi:[0,0,1]
	v_pk_mul_f32 v[12:13], v[12:13], v[46:47]
	v_pk_fma_f32 v[12:13], v[14:15], v[114:115], v[12:13]
	v_pk_add_f32 v[48:49], v[112:113], v[48:49]
	v_pk_add_f32 v[14:15], v[44:45], v[12:13]
	s_nop 0
	v_mov_b32_dpp v44, v48 row_shr:4 row_mask:0xf bank_mask:0xf bound_ctrl:1
	v_mov_b32_dpp v46, v14 row_shr:4 row_mask:0xf bank_mask:0xf bound_ctrl:1
	v_mov_b32_dpp v47, v15 row_shr:4 row_mask:0xf bank_mask:0xf bound_ctrl:1
	v_mov_b32_dpp v45, v49 row_shr:4 row_mask:0xf bank_mask:0xf bound_ctrl:1
	s_waitcnt lgkmcnt(0)
	v_pk_mul_f32 v[12:13], v[10:11], v[46:47]
	v_pk_mul_f32 v[46:47], v[8:9], v[46:47]
	v_pk_fma_f32 v[12:13], v[8:9], v[44:45], v[12:13] neg_lo:[0,0,1] neg_hi:[0,0,1]
	v_pk_fma_f32 v[44:45], v[10:11], v[44:45], v[46:47]
	v_pk_add_f32 v[12:13], v[48:49], v[12:13]
	v_pk_add_f32 v[44:45], v[14:15], v[44:45]
	v_mov_b32_dpp v14, v4 row_shr:8 row_mask:0xf bank_mask:0xf bound_ctrl:1
	v_mov_b32_dpp v46, v6 row_shr:8 row_mask:0xf bank_mask:0xf bound_ctrl:1
	v_mov_b32_dpp v15, v5 row_shr:8 row_mask:0xf bank_mask:0xf bound_ctrl:1
	v_mov_b32_dpp v47, v7 row_shr:8 row_mask:0xf bank_mask:0xf bound_ctrl:1
	v_mov_b32_dpp v48, v12 row_shr:8 row_mask:0xf bank_mask:0xf bound_ctrl:1
	v_mov_b32_dpp v50, v44 row_shr:8 row_mask:0xf bank_mask:0xf bound_ctrl:1
	v_mov_b32_dpp v49, v13 row_shr:8 row_mask:0xf bank_mask:0xf bound_ctrl:1
	v_mov_b32_dpp v51, v45 row_shr:8 row_mask:0xf bank_mask:0xf bound_ctrl:1
	s_and_saveexec_b64 s[0:1], s[8:9]
	s_cbranch_execz .LBB0_520
; #define SSM_SCAN_STEP(D, SQ) { _Pragma("unroll") for (int r = 0; r < 4; ++r) { \
;                     const float sr = dppf<DPP_SHR(D)>(Er[r]), si = dppf<DPP_SHR(D)>(Ei[r]); \
;                     Er[r] += mr[r] * sr - mi[r] * si; Ei[r] += mr[r] * si + mi[r] * sr; \
;                     if (SQ) { const float nr = mr[r] * mr[r] - mi[r] * mi[r], ni = 2.f * mr[r] * mi[r]; mr[r] = nr; mi[r] = ni; } } }
; template <bool PASS2>
; __device__ __forceinline__ void ssm_phase(const Params& p, const Frame& F0) {
;     ...
;                 SSM_SCAN_STEP(1, 1) SSM_SCAN_STEP(2, 1) SSM_SCAN_STEP(4, 1) SSM_SCAN_STEP(8, 0)
;     ...
;         if constexpr (!PASS2) { if (j == 15) { float* wb = Wst + (size_t)((g * 2 + b) * 32 + wch) * 128;
; #pragma unroll
;                 for (int i = 0; i < 4; ++i) { *(f32x4*)(wb + 16 * i + 4 * gq) = xs[i]; *(f32x4*)(wb + 64 + 16 * i + 4 * gq) = xs[i + 4]; } } }
	v_pk_mul_f32 v[112:113], v[54:55], v[54:55]
	v_pk_add_f32 v[110:111], v[52:53], v[52:53]
	v_pk_mul_f32 v[116:117], v[90:91], v[90:91]
	v_pk_fma_f32 v[112:113], v[52:53], v[52:53], v[112:113] neg_lo:[0,0,1] neg_hi:[0,0,1]
	v_pk_add_f32 v[114:115], v[88:89], v[88:89]
	v_pk_mul_f32 v[110:111], v[54:55], v[110:111]
	v_pk_fma_f32 v[88:89], v[88:89], v[88:89], v[116:117] neg_lo:[0,0,1] neg_hi:[0,0,1]
	v_pk_mul_f32 v[52:53], v[112:113], v[100:101]
	v_pk_mul_f32 v[90:91], v[90:91], v[114:115]
	v_pk_mul_f32 v[54:55], v[88:89], v[102:103]
	v_pk_fma_f32 v[52:53], v[110:111], v[94:95], v[52:53]
	v_pk_fma_f32 v[54:55], v[90:91], v[98:99], v[54:55]
	v_pk_add_f32 v[52:53], v[58:59], v[52:53]
	v_pk_mul_f32 v[58:59], v[110:111], v[100:101]
	v_pk_mul_f32 v[90:91], v[90:91], v[102:103]
	v_pk_fma_f32 v[58:59], v[112:113], v[94:95], v[58:59] neg_lo:[0,0,1] neg_hi:[0,0,1]
	v_pk_fma_f32 v[88:89], v[88:89], v[98:99], v[90:91] neg_lo:[0,0,1] neg_hi:[0,0,1]
	v_pk_mul_f32 v[90:91], v[62:63], v[62:63]
	v_pk_add_f32 v[56:57], v[56:57], v[58:59]
	v_pk_add_f32 v[58:59], v[92:93], v[88:89]
	v_pk_add_f32 v[88:89], v[60:61], v[60:61]
	v_pk_mul_f32 v[94:95], v[74:75], v[74:75]
	v_pk_fma_f32 v[90:91], v[60:61], v[60:61], v[90:91] neg_lo:[0,0,1] neg_hi:[0,0,1]
	v_pk_add_f32 v[92:93], v[72:73], v[72:73]
	v_pk_mul_f32 v[88:89], v[62:63], v[88:89]
	v_pk_fma_f32 v[72:73], v[72:73], v[72:73], v[94:95] neg_lo:[0,0,1] neg_hi:[0,0,1]
	v_pk_mul_f32 v[60:61], v[90:91], v[84:85]
	v_pk_mul_f32 v[74:75], v[74:75], v[92:93]
	v_pk_mul_f32 v[62:63], v[72:73], v[86:87]
	v_pk_fma_f32 v[60:61], v[88:89], v[78:79], v[60:61]
	v_pk_fma_f32 v[62:63], v[74:75], v[82:83], v[62:63]
	v_pk_add_f32 v[60:61], v[68:69], v[60:61]
	v_pk_mul_f32 v[68:69], v[88:89], v[84:85]
	v_pk_mul_f32 v[74:75], v[74:75], v[86:87]
	v_pk_fma_f32 v[68:69], v[90:91], v[78:79], v[68:69] neg_lo:[0,0,1] neg_hi:[0,0,1]
	v_pk_fma_f32 v[72:73], v[72:73], v[82:83], v[74:75] neg_lo:[0,0,1] neg_hi:[0,0,1]
	v_pk_mul_f32 v[74:75], v[18:19], v[18:19]
	v_pk_add_f32 v[66:67], v[66:67], v[68:69]
	v_pk_add_f32 v[68:69], v[76:77], v[72:73]
	v_pk_add_f32 v[72:73], v[16:17], v[16:17]
	v_pk_mul_f32 v[78:79], v[26:27], v[26:27]
	v_pk_fma_f32 v[74:75], v[16:17], v[16:17], v[74:75] neg_lo:[0,0,1] neg_hi:[0,0,1]
	v_pk_add_f32 v[76:77], v[24:25], v[24:25]
	v_pk_mul_f32 v[72:73], v[18:19], v[72:73]
	v_pk_fma_f32 v[24:25], v[24:25], v[24:25], v[78:79] neg_lo:[0,0,1] neg_hi:[0,0,1]
	v_pk_mul_f32 v[16:17], v[74:75], v[64:65]
	v_pk_mul_f32 v[26:27], v[26:27], v[76:77]
	v_pk_mul_f32 v[18:19], v[24:25], v[70:71]
	v_pk_fma_f32 v[16:17], v[72:73], v[30:31], v[16:17]
	v_pk_fma_f32 v[18:19], v[26:27], v[34:35], v[18:19]
	v_pk_add_f32 v[16:17], v[22:23], v[16:17]
	v_pk_mul_f32 v[22:23], v[72:73], v[64:65]
	v_pk_mul_f32 v[26:27], v[26:27], v[70:71]
	v_pk_fma_f32 v[22:23], v[74:75], v[30:31], v[22:23] neg_lo:[0,0,1] neg_hi:[0,0,1]
	v_pk_fma_f32 v[24:25], v[24:25], v[34:35], v[26:27] neg_lo:[0,0,1] neg_hi:[0,0,1]
	v_pk_mul_f32 v[30:31], v[2:3], v[2:3]
	v_pk_add_f32 v[20:21], v[20:21], v[22:23]
	v_pk_add_f32 v[22:23], v[28:29], v[24:25]
	v_pk_mul_f32 v[26:27], v[10:11], v[10:11]
	v_pk_add_f32 v[28:29], v[0:1], v[0:1]
	v_pk_fma_f32 v[30:31], v[0:1], v[0:1], v[30:31] neg_lo:[0,0,1] neg_hi:[0,0,1]
	s_lshl_b32 s10, s16, 6
	s_lshl_b32 s16, s17, 5
	v_pk_add_f32 v[24:25], v[8:9], v[8:9]
	v_pk_mul_f32 v[28:29], v[2:3], v[28:29]
	v_pk_fma_f32 v[8:9], v[8:9], v[8:9], v[26:27] neg_lo:[0,0,1] neg_hi:[0,0,1]
	v_pk_mul_f32 v[0:1], v[30:31], v[46:47]
	s_add_i32 s16, s18, s16
	v_pk_mul_f32 v[10:11], v[10:11], v[24:25]
	v_pk_mul_f32 v[2:3], v[8:9], v[50:51]
	v_pk_fma_f32 v[0:1], v[28:29], v[14:15], v[0:1]
	s_add_i32 s16, s16, s10
	v_pk_fma_f32 v[2:3], v[10:11], v[48:49], v[2:3]
	v_pk_add_f32 v[0:1], v[6:7], v[0:1]
	v_pk_mul_f32 v[6:7], v[28:29], v[46:47]
	v_pk_mul_f32 v[10:11], v[10:11], v[50:51]
	s_ashr_i32 s17, s16, 31
	v_pk_fma_f32 v[6:7], v[30:31], v[14:15], v[6:7] neg_lo:[0,0,1] neg_hi:[0,0,1]
	v_pk_fma_f32 v[8:9], v[8:9], v[48:49], v[10:11] neg_lo:[0,0,1] neg_hi:[0,0,1]
	s_lshl_b64 s[16:17], s[16:17], 9
	v_pk_add_f32 v[4:5], v[4:5], v[6:7]
	v_pk_add_f32 v[6:7], v[12:13], v[8:9]
	v_lshl_add_u64 v[8:9], v[40:41], 0, s[16:17]
	v_pk_add_f32 v[54:55], v[96:97], v[54:55]
	v_pk_add_f32 v[62:63], v[80:81], v[62:63]
	v_pk_add_f32 v[18:19], v[32:33], v[18:19]
	v_pk_add_f32 v[2:3], v[44:45], v[2:3]
	global_store_dwordx4 v[8:9], v[20:23], off
	global_store_dwordx4 v[8:9], v[16:19], off offset:256
	global_store_dwordx4 v[8:9], v[66:69], off offset:64
	global_store_dwordx4 v[8:9], v[60:63], off offset:320
	global_store_dwordx4 v[8:9], v[56:59], off offset:128
	global_store_dwordx4 v[8:9], v[52:55], off offset:384
	global_store_dwordx4 v[8:9], v[4:7], off offset:192
	global_store_dwordx4 v[8:9], v[0:3], off offset:448
	s_branch .LBB0_520
